# strategy instruction-selection: attention K/Q rms-norm 16-lane butterflies use DPP moves instead of four serialized ds_bpermute round trips each
# baseline (speedup 1.0000x reference)
; #define LAS __attribute__((address_space(3)))
; __device__ __forceinline__ float bflo(unsigned w) { return __uint_as_float(w << 16); }
; __device__ __forceinline__ float bfhi(unsigned w) { return __uint_as_float(w & 0xffff0000u); }
; __device__ __forceinline__ void attn_unit(int b, int h, int qb, const bf16_t* __restrict__ QK, const bf16_t* __restrict__ VT, bf16_t* __restrict__ O, const float* __restrict__ qg, const float* __restrict__ kg, ...
;     const int r32 = lane & 31, hi = lane >> 5;
;     const int q0 = qb * 256, NT = (q0 + 256) / 64;
;     LAS unsigned char* Kb = lds; LAS unsigned char* Vb = lds + 2 * AK_BUF;
;     LAS unsigned* flags = (LAS unsigned*)(lds + 2 * AK_BUF + 2 * AV_BUF);
;     const int kc0 = tid, kc1 = tid + 512;
;     const bf16_t* kg0 = QK + (size_t)(b * SEQ + (kc0 >> 4)) * 4096 + 2048 + h * HD + (kc0 & 15) * 8;
;     const bf16_t* kg1 = QK + (size_t)(b * SEQ + (kc1 >> 4)) * 4096 + 2048 + h * HD + (kc1 & 15) * 8;
;     const bf16_t* vg0 = VT + (size_t)(h * HD + (kc0 >> 3)) * MTOK + b * SEQ + (kc0 & 7) * 8;
;     const bf16_t* vg1 = VT + (size_t)(h * HD + (kc1 >> 3)) * MTOK + b * SEQ + (kc1 & 7) * 8;
;     const int kl0 = (kc0 >> 4) * AK_ROWB + (kc0 & 15) * 16, kl1 = (kc1 >> 4) * AK_ROWB + (kc1 & 15) * 16;
;     const int vl0 = (kc0 >> 3) * AV_ROWB + (kc0 & 7) * 16, vl1 = (kc1 >> 3) * AV_ROWB + (kc1 & 7) * 16;
;     const f32x4 kga = *(const f32x4*)(kg + (tid & 15) * 8), kgb = *(const f32x4*)(kg + (tid & 15) * 8 + 4);
;     const int tq = q0 + wid * 32 + r32;
;     bf16x8 qr[8];
;     { const bf16_t* qp = QK + (size_t)(b * SEQ + tq) * 4096 + h * HD + hi * 8;
;       u32x4 raw[8]; float ss = 0.f;
; #pragma unroll
;       for (int ks = 0; ks < 8; ++ks) { raw[ks] = *(const u32x4*)(qp + ks * 16);
; #pragma unroll
;           for (int q = 0; q < 4; ++q) { const float a = bflo(raw[ks][q]), c = bfhi(raw[ks][q]); ss += a * a + c * c; } }
.LBB0_463:
	s_ashr_i32 s3, s25, 31
	s_ashr_i32 s2, s25, 2
	s_lshr_b32 s3, s3, 28
	s_add_i32 s12, s2, s3
	s_and_b32 s3, s12, 0x1fffff0
	s_sub_i32 s13, s2, s3
	s_lshl_b32 s2, s25, 8
	s_and_b32 s2, s2, 0x300
	s_xor_b32 s3, s2, 0x700
	s_lshl_b32 s12, s12, 7
	s_add_i32 s23, s3, s47
	s_and_b32 s12, s12, 0xfffff800
	v_or_b32_e32 v173, s23, v154
	v_add_u32_e32 v0, s12, v173
	s_lshl_b32 s16, s13, 7
	v_ashrrev_i32_e32 v1, 31, v0
	s_ashr_i32 s17, s16, 31
	v_lshlrev_b64 v[0:1], 13, v[0:1]
	s_lshl_b64 s[14:15], s[16:17], 1
	v_lshl_add_u64 v[0:1], s[8:9], 0, v[0:1]
	v_lshl_add_u64 v[0:1], v[0:1], 0, s[14:15]
	v_mov_b32_e32 v169, v97
	v_lshl_add_u64 v[34:35], v[0:1], 0, v[168:169]
	global_load_dwordx4 v[44:47], v[34:35], off offset:224
	global_load_dwordx4 v[66:69], v[34:35], off offset:192
	global_load_dwordx4 v[74:77], v[34:35], off offset:160
	global_load_dwordx4 v[98:101], v[158:159], off offset:16
	global_load_dwordx4 v[102:105], v[158:159], off
	global_load_dwordx4 v[36:39], v[162:163], off offset:16
	global_load_dwordx4 v[40:43], v[162:163], off
	global_load_dwordx4 v[24:27], v[162:163], off offset:80
	global_load_dwordx4 v[28:31], v[162:163], off offset:64
	global_load_dwordx4 v[16:19], v[162:163], off offset:144
	global_load_dwordx4 v[20:23], v[162:163], off offset:128
	global_load_dwordx4 v[82:85], v[34:35], off offset:128
	global_load_dwordx4 v[8:11], v[162:163], off offset:208
	global_load_dwordx4 v[12:15], v[162:163], off offset:192
	global_load_dwordx4 v[0:3], v[162:163], off offset:272
	global_load_dwordx4 v[4:7], v[162:163], off offset:256
	global_load_dwordx4 v[106:109], v[34:35], off offset:64
	global_load_dwordx4 v[90:93], v[34:35], off offset:96
	global_load_dwordx4 v[114:117], v[34:35], off
	global_load_dwordx4 v[124:127], v[34:35], off offset:32
	v_add_u32_e32 v32, s12, v155
	v_add_u32_e32 v48, s12, v185
	v_ashrrev_i32_e32 v33, 31, v32
	v_ashrrev_i32_e32 v49, 31, v48
	v_add_u32_e32 v50, s16, v186
	v_add_u32_e32 v52, s16, v187
	v_lshlrev_b64 v[32:33], 13, v[32:33]
	v_lshlrev_b64 v[48:49], 13, v[48:49]
	v_ashrrev_i32_e32 v51, 31, v50
	v_ashrrev_i32_e32 v53, 31, v52
	s_ashr_i32 s13, s12, 31
	v_lshl_add_u64 v[54:55], s[8:9], 0, v[32:33]
	v_lshl_add_u64 v[48:49], s[8:9], 0, v[48:49]
	v_lshlrev_b64 v[32:33], 14, v[50:51]
	v_lshlrev_b64 v[50:51], 14, v[52:53]
	v_mov_b32_e32 v171, v97
	s_lshl_b64 s[16:17], s[12:13], 1
	v_lshl_add_u64 v[56:57], v[48:49], 0, s[14:15]
	v_lshl_add_u64 v[48:49], s[10:11], 0, v[50:51]
	v_lshl_add_u64 v[50:51], v[54:55], 0, s[14:15]
	v_lshl_add_u64 v[48:49], v[48:49], 0, s[16:17]
	v_lshl_add_u64 v[50:51], v[50:51], 0, v[170:171]
	s_mov_b64 s[28:29], 0x1000
	v_lshl_add_u64 v[176:177], v[48:49], 0, v[96:97]
	v_lshl_add_u64 v[178:179], v[50:51], 0, s[28:29]
	v_lshl_add_u64 v[32:33], s[10:11], 0, v[32:33]
	s_add_i32 s24, s3, 0x100
	s_or_b32 s13, s23, 31
	s_waitcnt vmcnt(0)
	v_and_b32_e32 v49, 0xffff0000, v47
	v_and_b32_e32 v51, 0xffff0000, v46
	v_and_b32_e32 v53, 0xffff0000, v45
	v_and_b32_e32 v55, 0xffff0000, v44
	v_lshlrev_b32_e32 v48, 16, v47
	v_lshlrev_b32_e32 v50, 16, v46
	v_lshlrev_b32_e32 v212, 16, v115
	v_and_b32_e32 v213, 0xffff0000, v115
	v_lshlrev_b32_e32 v216, 16, v114
	v_and_b32_e32 v217, 0xffff0000, v114
	v_lshlrev_b32_e32 v210, 16, v116
	v_and_b32_e32 v211, 0xffff0000, v116
	v_pk_mul_f32 v[214:215], v[212:213], v[212:213]
	v_pk_mul_f32 v[114:115], v[216:217], v[216:217]
	v_lshlrev_b32_e32 v198, 16, v117
	v_and_b32_e32 v199, 0xffff0000, v117
	v_pk_mul_f32 v[116:117], v[210:211], v[210:211]
	v_add_f32_e32 v175, v214, v215
	v_add_f32_e32 v114, v114, v115
	v_lshlrev_b32_e32 v196, 16, v124
	v_and_b32_e32 v197, 0xffff0000, v124
	v_pk_mul_f32 v[200:201], v[198:199], v[198:199]
	v_add_f32_e32 v114, v114, v175
	v_add_f32_e32 v115, v116, v117
	v_lshlrev_b32_e32 v122, 16, v125
	v_and_b32_e32 v123, 0xffff0000, v125
	v_pk_mul_f32 v[124:125], v[196:197], v[196:197]
	v_add_f32_e32 v169, v200, v201
	v_add_f32_e32 v114, v115, v114
	v_lshlrev_b32_e32 v112, 16, v126
	v_and_b32_e32 v113, 0xffff0000, v126
	v_pk_mul_f32 v[194:195], v[122:123], v[122:123]
	v_add_f32_e32 v114, v169, v114
	v_add_f32_e32 v115, v124, v125
	v_lshlrev_b32_e32 v52, 16, v45
	v_lshlrev_b32_e32 v54, 16, v44
	v_and_b32_e32 v59, 0xffff0000, v69
	v_and_b32_e32 v61, 0xffff0000, v68
	v_mov_b32_e32 v44, v49
	v_mov_b32_e32 v45, v51
	v_mov_b32_e32 v62, v53
	v_mov_b32_e32 v63, v55
	v_lshlrev_b32_e32 v120, 16, v127
	v_and_b32_e32 v121, 0xffff0000, v127
	v_pk_mul_f32 v[126:127], v[112:113], v[112:113]
	v_add_f32_e32 v114, v115, v114
	v_add_f32_e32 v115, v194, v195
	v_lshlrev_b32_e32 v58, 16, v69
	v_lshlrev_b32_e32 v60, 16, v68
	v_mov_b32_e32 v34, v48
	v_mov_b32_e32 v35, v50
	v_mov_b32_e32 v46, v52
	v_mov_b32_e32 v47, v54
	v_mov_b32_e32 v68, v59
	v_pk_mul_f32 v[44:45], v[44:45], v[44:45]
	v_pk_mul_f32 v[62:63], v[62:63], v[62:63]
	v_mov_b32_e32 v69, v61
	v_lshlrev_b32_e32 v118, 16, v106
	v_and_b32_e32 v119, 0xffff0000, v106
	v_pk_mul_f32 v[192:193], v[120:121], v[120:121]
	v_add_f32_e32 v114, v115, v114
	v_add_f32_e32 v115, v126, v127
	v_mov_b32_e32 v64, v58
	v_mov_b32_e32 v65, v60
	v_pk_fma_f32 v[34:35], v[34:35], v[34:35], v[44:45]
	v_pk_fma_f32 v[44:45], v[46:47], v[46:47], v[62:63]
	v_pk_mul_f32 v[46:47], v[68:69], v[68:69]
	v_lshlrev_b32_e32 v94, 16, v107
	v_and_b32_e32 v95, 0xffff0000, v107
	v_pk_mul_f32 v[106:107], v[118:119], v[118:119]
	v_add_f32_e32 v114, v115, v114
	v_add_f32_e32 v115, v192, v193
	v_pk_fma_f32 v[46:47], v[64:65], v[64:65], v[46:47]
	v_lshlrev_b32_e32 v62, 16, v67
	v_and_b32_e32 v63, 0xffff0000, v67
	v_lshlrev_b32_e32 v64, 16, v66
	v_and_b32_e32 v65, 0xffff0000, v66
	v_lshlrev_b32_e32 v66, 16, v77
	v_and_b32_e32 v67, 0xffff0000, v77
; __device__ __forceinline__ unsigned pk2(float lo, float hi) { f32x2 v = {lo, hi}; bf16x2_t b = __builtin_convertvector(v, bf16x2_t); return __builtin_bit_cast(unsigned, b); }
; __device__ __forceinline__ float bflo(unsigned w) { return __uint_as_float(w << 16); }
; __device__ __forceinline__ float bfhi(unsigned w) { return __uint_as_float(w & 0xffff0000u); }
; __device__ __forceinline__ void attn_unit(int b, int h, int qb, const bf16_t* __restrict__ QK, const bf16_t* __restrict__ VT, bf16_t* __restrict__ O, const float* __restrict__ qg, const float* __restrict__ kg, ...
;     ...
;           for (int q = 0; q < 4; ++q) { const float a = bflo(raw[ks][q]), c = bfhi(raw[ks][q]); ss += a * a + c * c; } }
;       ss += __shfl_xor(ss, 32);
;       const float r = __builtin_amdgcn_rsqf(ss * (1.0f / HD) + RMS_EPS) * (1.4426950408889634f * 0.08838834764831845f);
; #pragma unroll
;       for (int ks = 0; ks < 8; ++ks) { const f32x4 ga = *(const f32x4*)(qg + ks * 16 + hi * 8), gb = *(const f32x4*)(qg + ks * 16 + hi * 8 + 4); u32x4 o;
;           o.x = pk2(bflo(raw[ks][0]) * r * ga[0], bfhi(raw[ks][0]) * r * ga[1]); o.y = pk2(bflo(raw[ks][1]) * r * ga[2], bfhi(raw[ks][1]) * r * ga[3]);
;           o.z = pk2(bflo(raw[ks][2]) * r * gb[0], bfhi(raw[ks][2]) * r * gb[1]); o.w = pk2(bflo(raw[ks][3]) * r * gb[2], bfhi(raw[ks][3]) * r * gb[3]);
;           qr[ks] = __builtin_bit_cast(bf16x8, o); } }
;     const int krow = 16 * ((r32 >> 2) & 1) + (r32 & 3) + 4 * (r32 >> 3);
;     const int kfo = krow * AK_ROWB + hi * 16, vfo = r32 * AV_ROWB + hi * 32;
;     f32x16 o[4];
; #pragma unroll
;     for (int d = 0; d < 4; ++d)
; #pragma unroll
;         for (int r = 0; r < 16; ++r) o[d][r] = 0.f;
;     float R = 0.f; bool wdone = false;
;     u32x4 sk0, sk1, sv0, sv1;
;     { const int kt = NT - 1; sk0 = *(const u32x4*)(kg0 + (size_t)kt * 64 * 4096); sk1 = *(const u32x4*)(kg1 + (size_t)kt * 64 * 4096); sv0 = *(const u32x4*)(vg0 + kt * 64); sv1 = *(const u32x4*)(vg1 + kt * 64); }
	v_lshlrev_b32_e32 v68, 16, v76
	v_and_b32_e32 v69, 0xffff0000, v76
	v_lshlrev_b32_e32 v70, 16, v75
	v_and_b32_e32 v71, 0xffff0000, v75
	v_lshlrev_b32_e32 v72, 16, v74
	v_and_b32_e32 v73, 0xffff0000, v74
	v_lshlrev_b32_e32 v74, 16, v85
	v_and_b32_e32 v75, 0xffff0000, v85
	v_lshlrev_b32_e32 v76, 16, v84
	v_and_b32_e32 v77, 0xffff0000, v84
	v_lshlrev_b32_e32 v78, 16, v83
	v_and_b32_e32 v79, 0xffff0000, v83
	v_lshlrev_b32_e32 v80, 16, v82
	v_and_b32_e32 v81, 0xffff0000, v82
	v_lshlrev_b32_e32 v82, 16, v93
	v_and_b32_e32 v83, 0xffff0000, v93
	v_lshlrev_b32_e32 v84, 16, v92
	v_and_b32_e32 v85, 0xffff0000, v92
	v_lshlrev_b32_e32 v92, 16, v108
	v_and_b32_e32 v93, 0xffff0000, v108
	v_pk_mul_f32 v[182:183], v[94:95], v[94:95]
	v_add_f32_e32 v114, v115, v114
	v_add_f32_e32 v106, v106, v107
	v_lshlrev_b32_e32 v86, 16, v91
	v_and_b32_e32 v87, 0xffff0000, v91
	v_lshlrev_b32_e32 v88, 16, v90
	v_and_b32_e32 v89, 0xffff0000, v90
	v_lshlrev_b32_e32 v90, 16, v109
	v_and_b32_e32 v91, 0xffff0000, v109
	v_pk_mul_f32 v[108:109], v[92:93], v[92:93]
	v_add_f32_e32 v106, v106, v114
	v_add_f32_e32 v107, v182, v183
	v_pk_mul_f32 v[180:181], v[90:91], v[90:91]
	v_add_f32_e32 v106, v107, v106
	v_add_f32_e32 v107, v108, v109
	v_pk_mul_f32 v[152:153], v[88:89], v[88:89]
	v_add_f32_e32 v106, v107, v106
	v_add_f32_e32 v107, v180, v181
	v_pk_mul_f32 v[150:151], v[86:87], v[86:87]
	v_add_f32_e32 v106, v107, v106
	v_add_f32_e32 v107, v152, v153
	v_pk_mul_f32 v[148:149], v[84:85], v[84:85]
	v_add_f32_e32 v106, v107, v106
	v_add_f32_e32 v107, v150, v151
	v_pk_mul_f32 v[146:147], v[82:83], v[82:83]
	v_add_f32_e32 v106, v107, v106
	v_add_f32_e32 v107, v148, v149
	v_pk_mul_f32 v[144:145], v[80:81], v[80:81]
	v_add_f32_e32 v106, v107, v106
	v_add_f32_e32 v107, v146, v147
	v_pk_mul_f32 v[142:143], v[78:79], v[78:79]
	v_add_f32_e32 v106, v107, v106
	v_add_f32_e32 v107, v144, v145
	v_pk_mul_f32 v[140:141], v[76:77], v[76:77]
	v_add_f32_e32 v106, v107, v106
	v_add_f32_e32 v107, v142, v143
	v_pk_mul_f32 v[138:139], v[74:75], v[74:75]
	v_add_f32_e32 v106, v107, v106
	v_add_f32_e32 v107, v140, v141
	v_pk_mul_f32 v[136:137], v[72:73], v[72:73]
	v_add_f32_e32 v106, v107, v106
	v_add_f32_e32 v107, v138, v139
	v_pk_mul_f32 v[134:135], v[70:71], v[70:71]
	v_add_f32_e32 v106, v107, v106
	v_add_f32_e32 v107, v136, v137
	v_pk_mul_f32 v[132:133], v[68:69], v[68:69]
	v_add_f32_e32 v106, v107, v106
	v_add_f32_e32 v107, v134, v135
	v_pk_mul_f32 v[130:131], v[66:67], v[66:67]
	v_add_f32_e32 v106, v107, v106
	v_add_f32_e32 v107, v132, v133
	v_pk_mul_f32 v[128:129], v[64:65], v[64:65]
	v_add_f32_e32 v106, v107, v106
	v_add_f32_e32 v107, v130, v131
	v_pk_mul_f32 v[110:111], v[62:63], v[62:63]
	v_add_f32_e32 v106, v107, v106
	v_add_f32_e32 v107, v128, v129
	v_add_f32_e32 v106, v107, v106
	v_add_f32_e32 v107, v110, v111
	v_add_f32_e32 v106, v107, v106
	v_add_f32_e32 v47, v47, v106
	v_add_f32_e32 v46, v46, v47
	v_add_f32_e32 v45, v45, v46
	v_add_f32_e32 v44, v44, v45
	v_add_f32_e32 v35, v35, v44
	v_add_f32_e32 v34, v34, v35
	ds_bpermute_b32 v35, v157, v34
	v_lshl_add_u64 v[142:143], v[32:33], 0, s[16:17]
	global_load_dwordx4 v[136:139], v[162:163], off offset:336
	global_load_dwordx4 v[144:147], v[162:163], off offset:320
	s_lshr_b32 s16, s24, 6
	s_add_i32 s18, s16, -1
	s_waitcnt lgkmcnt(0)
	v_add_f32_e32 v32, v34, v35
	v_fmamk_f32 v32, v32, 0x3c000000, v243
	v_rsq_f32_e32 v106, v32
	s_lshl_b64 s[26:27], s[18:19], 19
	global_load_dwordx4 v[148:151], v[162:163], off offset:400
	global_load_dwordx4 v[192:195], v[162:163], off offset:384
	global_load_dwordx4 v[32:35], v[162:163], off offset:464
	global_load_dwordx4 v[44:47], v[162:163], off offset:448
	v_lshl_add_u64 v[182:183], v[142:143], 0, v[96:97]
	v_mul_f32_e32 v184, 0x3e0293ee, v106
	v_pk_mul_f32 v[106:107], v[184:185], v[216:217] op_sel_hi:[0,1]
	v_pk_mul_f32 v[40:41], v[40:41], v[106:107]
	s_lshl_b32 s18, s18, 7
	v_cvt_pk_bf16_f32 v106, v40, v41
	v_pk_mul_f32 v[40:41], v[184:185], v[212:213] op_sel_hi:[0,1]
	v_pk_mul_f32 v[40:41], v[42:43], v[40:41]
	s_add_i32 s34, s16, -2
	v_cvt_pk_bf16_f32 v107, v40, v41
	v_pk_mul_f32 v[40:41], v[184:185], v[210:211] op_sel_hi:[0,1]
	v_pk_mul_f32 v[36:37], v[36:37], v[40:41]
	s_mov_b64 s[16:17], 0
	v_cvt_pk_bf16_f32 v108, v36, v37
	v_pk_mul_f32 v[36:37], v[184:185], v[198:199] op_sel_hi:[0,1]
	v_pk_mul_f32 v[36:37], v[38:39], v[36:37]
	v_lshl_add_u64 v[38:39], v[178:179], 0, s[26:27]
	global_load_dwordx4 v[114:117], v[38:39], off
	v_cvt_pk_bf16_f32 v109, v36, v37
	v_pk_mul_f32 v[36:37], v[184:185], v[196:197] op_sel_hi:[0,1]
	v_pk_mul_f32 v[28:29], v[28:29], v[36:37]
	v_mov_b32_e32 v169, 0
	v_cvt_pk_bf16_f32 v110, v28, v29
	v_pk_mul_f32 v[28:29], v[184:185], v[122:123] op_sel_hi:[0,1]
	v_pk_mul_f32 v[28:29], v[30:31], v[28:29]
	s_nop 0
	v_cvt_pk_bf16_f32 v111, v28, v29
	v_pk_mul_f32 v[28:29], v[184:185], v[112:113] op_sel_hi:[0,1]
	v_pk_mul_f32 v[24:25], v[24:25], v[28:29]
	s_nop 0
	v_cvt_pk_bf16_f32 v112, v24, v25
	v_pk_mul_f32 v[24:25], v[184:185], v[120:121] op_sel_hi:[0,1]
	v_pk_mul_f32 v[24:25], v[26:27], v[24:25]
	s_nop 0
	v_cvt_pk_bf16_f32 v113, v24, v25
	v_pk_mul_f32 v[24:25], v[184:185], v[118:119] op_sel_hi:[0,1]
	v_pk_mul_f32 v[20:21], v[20:21], v[24:25]
	s_nop 0
	v_cvt_pk_bf16_f32 v118, v20, v21
	v_pk_mul_f32 v[20:21], v[184:185], v[94:95] op_sel_hi:[0,1]
	v_pk_mul_f32 v[20:21], v[22:23], v[20:21]
	s_nop 0
	v_cvt_pk_bf16_f32 v119, v20, v21
	v_pk_mul_f32 v[20:21], v[184:185], v[92:93] op_sel_hi:[0,1]
	v_pk_mul_f32 v[16:17], v[16:17], v[20:21]
	s_nop 0
	v_cvt_pk_bf16_f32 v120, v16, v17
	v_pk_mul_f32 v[16:17], v[184:185], v[90:91] op_sel_hi:[0,1]
	v_pk_mul_f32 v[16:17], v[18:19], v[16:17]
	s_nop 0
	v_cvt_pk_bf16_f32 v121, v16, v17
	v_pk_mul_f32 v[16:17], v[184:185], v[88:89] op_sel_hi:[0,1]
	v_pk_mul_f32 v[12:13], v[12:13], v[16:17]
	s_nop 0
	v_cvt_pk_bf16_f32 v122, v12, v13
	v_pk_mul_f32 v[12:13], v[184:185], v[86:87] op_sel_hi:[0,1]
	v_pk_mul_f32 v[12:13], v[14:15], v[12:13]
	s_nop 0
	v_cvt_pk_bf16_f32 v123, v12, v13
	v_pk_mul_f32 v[12:13], v[184:185], v[84:85] op_sel_hi:[0,1]
	v_pk_mul_f32 v[8:9], v[8:9], v[12:13]
	s_nop 0
	v_cvt_pk_bf16_f32 v124, v8, v9
	v_pk_mul_f32 v[8:9], v[184:185], v[82:83] op_sel_hi:[0,1]
	v_pk_mul_f32 v[8:9], v[10:11], v[8:9]
	v_lshl_add_u64 v[10:11], v[56:57], 0, v[170:171]
	v_lshl_add_u64 v[180:181], v[10:11], 0, s[28:29]
	v_lshl_add_u64 v[10:11], v[180:181], 0, s[26:27]
	global_load_dwordx4 v[130:133], v[10:11], off
	v_cvt_pk_bf16_f32 v125, v8, v9
	v_pk_mul_f32 v[8:9], v[184:185], v[80:81] op_sel_hi:[0,1]
	v_pk_mul_f32 v[4:5], v[4:5], v[8:9]
	v_add_u32_e32 v171, 0, v164
	v_cvt_pk_bf16_f32 v126, v4, v5
	v_pk_mul_f32 v[4:5], v[184:185], v[78:79] op_sel_hi:[0,1]
	v_pk_mul_f32 v[4:5], v[6:7], v[4:5]
	s_mov_b32 s26, 0
	v_cvt_pk_bf16_f32 v127, v4, v5
	v_pk_mul_f32 v[4:5], v[184:185], v[76:77] op_sel_hi:[0,1]
	v_pk_mul_f32 v[0:1], v[0:1], v[4:5]
	s_waitcnt vmcnt(1)
; #define LAS __attribute__((address_space(3)))
; __device__ __forceinline__ unsigned pk2(float lo, float hi) { f32x2 v = {lo, hi}; bf16x2_t b = __builtin_convertvector(v, bf16x2_t); return __builtin_bit_cast(unsigned, b); }
; __device__ __forceinline__ float bflo(unsigned w) { return __uint_as_float(w << 16); }
; __device__ __forceinline__ float bfhi(unsigned w) { return __uint_as_float(w & 0xffff0000u); }
; __device__ __forceinline__ u32x4 knorm8(u32x4 w, const f32x4 ga, const f32x4 gb) {
;     float v[8];
; #pragma unroll
;     for (int q = 0; q < 4; ++q) { v[2 * q] = bflo(w[q]); v[2 * q + 1] = bfhi(w[q]); }
;     float ss = 0.f;
; #pragma unroll
;     for (int e = 0; e < 8; ++e) ss += v[e] * v[e];
;     ss += __shfl_xor(ss, 1); ss += __shfl_xor(ss, 2); ss += __shfl_xor(ss, 4); ss += __shfl_xor(ss, 8);
;     const float r = __builtin_amdgcn_rsqf(ss * (1.0f / HD) + RMS_EPS);
;     u32x4 o; o.x = pk2(v[0] * r * ga[0], v[1] * r * ga[1]); o.y = pk2(v[2] * r * ga[2], v[3] * r * ga[3]); o.z = pk2(v[4] * r * gb[0], v[5] * r * gb[1]); o.w = pk2(v[6] * r * gb[2], v[7] * r * gb[3]);
;     return o;
; }
; __device__ __forceinline__ void attn_unit(int b, int h, int qb, const bf16_t* __restrict__ QK, const bf16_t* __restrict__ VT, bf16_t* __restrict__ O, const float* __restrict__ qg, const float* __restrict__ kg, ...
;     ...
;     f32x16 o[4];
; #pragma unroll
;     for (int d = 0; d < 4; ++d)
; #pragma unroll
;         for (int r = 0; r < 16; ++r) o[d][r] = 0.f;
;     float R = 0.f; bool wdone = false;
;     u32x4 sk0, sk1, sv0, sv1;
;     { const int kt = NT - 1; sk0 = *(const u32x4*)(kg0 + (size_t)kt * 64 * 4096); sk1 = *(const u32x4*)(kg1 + (size_t)kt * 64 * 4096); sv0 = *(const u32x4*)(vg0 + kt * 64); sv1 = *(const u32x4*)(vg1 + kt * 64); }
;     *(LAS u32x4*)(Kb + kl0) = knorm8(sk0, kga, kgb); *(LAS u32x4*)(Kb + kl1) = knorm8(sk1, kga, kgb); *(LAS u32x4*)(Vb + vl0) = sv0; *(LAS u32x4*)(Vb + vl1) = sv1;
;     __syncthreads();
;     int buf = 0;
	v_lshlrev_b32_e32 v14, 16, v114
	v_cvt_pk_bf16_f32 v128, v0, v1
	v_pk_mul_f32 v[0:1], v[184:185], v[74:75] op_sel_hi:[0,1]
	v_pk_mul_f32 v[0:1], v[2:3], v[0:1]
	v_and_b32_e32 v15, 0xffff0000, v114
	v_cvt_pk_bf16_f32 v129, v0, v1
	v_pk_mul_f32 v[0:1], v[184:185], v[72:73] op_sel_hi:[0,1]
	v_pk_mul_f32 v[0:1], v[144:145], v[0:1]
	v_lshlrev_b32_e32 v10, 16, v115
	v_cvt_pk_bf16_f32 v134, v0, v1
	v_pk_mul_f32 v[0:1], v[184:185], v[70:71] op_sel_hi:[0,1]
	v_pk_mul_f32 v[0:1], v[146:147], v[0:1]
	v_and_b32_e32 v11, 0xffff0000, v115
	v_cvt_pk_bf16_f32 v135, v0, v1
	v_pk_mul_f32 v[0:1], v[184:185], v[68:69] op_sel_hi:[0,1]
	v_pk_mul_f32 v[0:1], v[136:137], v[0:1]
	v_pk_mul_f32 v[16:17], v[14:15], v[14:15]
	v_cvt_pk_bf16_f32 v136, v0, v1
	v_pk_mul_f32 v[0:1], v[184:185], v[66:67] op_sel_hi:[0,1]
	v_pk_mul_f32 v[0:1], v[138:139], v[0:1]
	v_pk_mul_f32 v[12:13], v[10:11], v[10:11]
	v_add_f32_e32 v16, v16, v17
	v_cvt_pk_bf16_f32 v137, v0, v1
	v_pk_mul_f32 v[0:1], v[184:185], v[64:65] op_sel_hi:[0,1]
	v_lshlrev_b32_e32 v6, 16, v116
	v_and_b32_e32 v7, 0xffff0000, v116
	v_add_f32_e32 v12, v12, v16
	v_pk_mul_f32 v[0:1], v[192:193], v[0:1]
	v_pk_mul_f32 v[8:9], v[6:7], v[6:7]
	v_add_f32_e32 v12, v13, v12
	v_cvt_pk_bf16_f32 v138, v0, v1
	v_pk_mul_f32 v[0:1], v[184:185], v[62:63] op_sel_hi:[0,1]
	v_lshlrev_b32_e32 v4, 16, v117
	v_and_b32_e32 v5, 0xffff0000, v117
	v_add_f32_e32 v8, v8, v12
	v_pk_mul_f32 v[0:1], v[194:195], v[0:1]
	v_pk_mul_f32 v[2:3], v[4:5], v[4:5]
	v_add_f32_e32 v8, v9, v8
	v_cvt_pk_bf16_f32 v139, v0, v1
	v_pk_mul_f32 v[0:1], v[184:185], v[60:61] op_sel_hi:[0,1]
	v_add_f32_e32 v2, v2, v8
	v_pk_mul_f32 v[0:1], v[148:149], v[0:1]
	v_add_f32_e32 v8, v3, v2
	v_lshl_add_u64 v[2:3], v[182:183], 0, s[18:19]
	v_cvt_pk_bf16_f32 v140, v0, v1
	v_pk_mul_f32 v[0:1], v[184:185], v[58:59] op_sel_hi:[0,1]
	global_load_dwordx4 v[146:149], v[2:3], off
	v_lshl_add_u64 v[2:3], v[176:177], 0, s[18:19]
	v_pk_mul_f32 v[0:1], v[150:151], v[0:1]
	global_load_dwordx4 v[150:153], v[2:3], off
	s_nop 1
	v_mov_b32_dpp v9, v8 quad_perm:[1,0,3,2] row_mask:0xf bank_mask:0xf
	s_waitcnt vmcnt(2)
	v_lshlrev_b32_e32 v22, 16, v130
	v_and_b32_e32 v23, 0xffff0000, v130
	v_lshlrev_b32_e32 v18, 16, v131
	v_and_b32_e32 v19, 0xffff0000, v131
	s_waitcnt lgkmcnt(0)
	v_add_f32_e32 v2, v8, v9
	s_nop 1
	v_mov_b32_dpp v3, v2 quad_perm:[2,3,0,1] row_mask:0xf bank_mask:0xf
	v_pk_mul_f32 v[24:25], v[22:23], v[22:23]
	v_pk_mul_f32 v[20:21], v[18:19], v[18:19]
	v_add_f32_e32 v24, v24, v25
	v_lshlrev_b32_e32 v12, 16, v132
	s_waitcnt lgkmcnt(0)
	v_add_f32_e32 v2, v2, v3
	s_nop 1
	v_mov_b32_dpp v3, v2 row_shl:4 row_mask:0xf bank_mask:0x5
	v_mov_b32_dpp v3, v2 row_shr:4 row_mask:0xf bank_mask:0xa
	v_and_b32_e32 v13, 0xffff0000, v132
	v_add_f32_e32 v20, v20, v24
	v_pk_mul_f32 v[16:17], v[12:13], v[12:13]
	v_add_f32_e32 v20, v21, v20
	v_lshlrev_b32_e32 v8, 16, v133
	v_and_b32_e32 v9, 0xffff0000, v133
	v_add_f32_e32 v16, v16, v20
	s_waitcnt lgkmcnt(0)
	v_add_f32_e32 v26, v2, v3
	v_pk_mul_f32 v[2:3], v[8:9], v[8:9]
	v_add_f32_e32 v16, v17, v16
	v_add_f32_e32 v2, v2, v16
	v_add_f32_e32 v2, v3, v2
	s_nop 1
	v_mov_b32_dpp v27, v26 row_ror:8 row_mask:0xf bank_mask:0xf
	s_nop 1
	v_mov_b32_dpp v3, v2 quad_perm:[1,0,3,2] row_mask:0xf bank_mask:0xf
	v_cvt_pk_bf16_f32 v141, v0, v1
	v_pk_mul_f32 v[0:1], v[184:185], v[54:55] op_sel_hi:[0,1]
	v_pk_mul_f32 v[0:1], v[44:45], v[0:1]
	s_waitcnt lgkmcnt(1)
	v_add_f32_e32 v16, v26, v27
	v_cvt_pk_bf16_f32 v142, v0, v1
	v_pk_mul_f32 v[0:1], v[184:185], v[52:53] op_sel_hi:[0,1]
	s_waitcnt lgkmcnt(0)
	v_add_f32_e32 v2, v2, v3
	v_pk_mul_f32 v[0:1], v[46:47], v[0:1]
	v_fmamk_f32 v16, v16, 0x3c000000, v243
	s_nop 1
	v_mov_b32_dpp v3, v2 quad_perm:[2,3,0,1] row_mask:0xf bank_mask:0xf
	v_cvt_pk_bf16_f32 v143, v0, v1
	v_pk_mul_f32 v[0:1], v[184:185], v[50:51] op_sel_hi:[0,1]
	v_rsq_f32_e32 v16, v16
	v_pk_mul_f32 v[0:1], v[32:33], v[0:1]
	s_or_b32 s18, s3, 0x80
	v_cvt_pk_bf16_f32 v144, v0, v1
	v_pk_mul_f32 v[0:1], v[184:185], v[48:49] op_sel_hi:[0,1]
	v_pk_mul_f32 v[0:1], v[34:35], v[0:1]
	v_pk_mul_f32 v[4:5], v[16:17], v[4:5] op_sel_hi:[0,1]
	v_cvt_pk_bf16_f32 v145, v0, v1
	v_pk_mul_f32 v[0:1], v[16:17], v[14:15] op_sel_hi:[0,1]
	s_waitcnt lgkmcnt(0)
	v_add_f32_e32 v14, v2, v3
	s_nop 1
	v_mov_b32_dpp v15, v14 row_shl:4 row_mask:0xf bank_mask:0x5
	v_mov_b32_dpp v15, v14 row_shr:4 row_mask:0xf bank_mask:0xa
	v_pk_mul_f32 v[2:3], v[16:17], v[10:11] op_sel_hi:[0,1]
	v_pk_mul_f32 v[0:1], v[102:103], v[0:1]
	v_pk_mul_f32 v[2:3], v[104:105], v[2:3]
	v_cvt_pk_bf16_f32 v0, v0, v1
	v_cvt_pk_bf16_f32 v1, v2, v3
	v_pk_mul_f32 v[2:3], v[16:17], v[6:7] op_sel_hi:[0,1]
	s_waitcnt lgkmcnt(0)
	v_add_f32_e32 v6, v14, v15
	s_nop 1
	v_mov_b32_dpp v7, v6 row_ror:8 row_mask:0xf bank_mask:0xf
	v_pk_mul_f32 v[2:3], v[98:99], v[2:3]
	v_pk_mul_f32 v[4:5], v[100:101], v[4:5]
	v_cvt_pk_bf16_f32 v2, v2, v3
	v_add_u32_e32 v184, 0, v156
	s_waitcnt lgkmcnt(0)
	v_add_f32_e32 v3, v6, v7
	v_fmamk_f32 v3, v3, 0x3c000000, v243
	v_rsq_f32_e32 v6, v3
	v_cvt_pk_bf16_f32 v3, v4, v5
	ds_write_b128 v171, v[0:3]
	v_mov_b32_e32 v14, v97
	v_pk_mul_f32 v[0:1], v[6:7], v[22:23] op_sel_hi:[0,1]
	v_pk_mul_f32 v[2:3], v[6:7], v[18:19] op_sel_hi:[0,1]
	v_pk_mul_f32 v[0:1], v[102:103], v[0:1]
	v_pk_mul_f32 v[2:3], v[104:105], v[2:3]
	v_cvt_pk_bf16_f32 v0, v0, v1
	v_cvt_pk_bf16_f32 v1, v2, v3
	v_pk_mul_f32 v[2:3], v[6:7], v[12:13] op_sel_hi:[0,1]
	v_pk_mul_f32 v[4:5], v[6:7], v[8:9] op_sel_hi:[0,1]
	v_pk_mul_f32 v[2:3], v[98:99], v[2:3]
	v_pk_mul_f32 v[4:5], v[100:101], v[4:5]
	v_cvt_pk_bf16_f32 v2, v2, v3
	v_cvt_pk_bf16_f32 v3, v4, v5
	v_mov_b32_e32 v15, v97
	ds_write_b128 v184, v[0:3]
	s_lshr_b32 s3, s24, 3
	v_mov_b32_e32 v0, v97
	v_mov_b32_e32 v1, v97
	v_mov_b32_e32 v2, v97
	v_mov_b32_e32 v3, v97
	v_mov_b32_e32 v4, v97
	v_mov_b32_e32 v5, v97
	v_mov_b32_e32 v6, v97
	v_mov_b32_e32 v7, v97
	v_mov_b32_e32 v8, v97
	v_mov_b32_e32 v9, v97
	v_mov_b32_e32 v10, v97
	v_mov_b32_e32 v11, v97
	v_mov_b32_e32 v12, v97
	v_mov_b32_e32 v13, v97
	v_mov_b64_e32 v[62:63], v[14:15]
	v_mov_b64_e32 v[46:47], v[14:15]
	v_mov_b64_e32 v[30:31], v[14:15]
	v_add_u32_e32 v192, 0, v160
	v_add_u32_e32 v193, 0, v166
	s_add_i32 s24, s3, -8
	v_mov_b64_e32 v[60:61], v[12:13]
	v_mov_b64_e32 v[58:59], v[10:11]
	v_mov_b64_e32 v[56:57], v[8:9]
	v_mov_b64_e32 v[54:55], v[6:7]
	v_mov_b64_e32 v[52:53], v[4:5]
	v_mov_b64_e32 v[50:51], v[2:3]
	v_mov_b64_e32 v[48:49], v[0:1]
	v_mov_b64_e32 v[44:45], v[12:13]
	v_mov_b64_e32 v[42:43], v[10:11]
	v_mov_b64_e32 v[40:41], v[8:9]
	v_mov_b64_e32 v[38:39], v[6:7]
	v_mov_b64_e32 v[36:37], v[4:5]
	v_mov_b64_e32 v[34:35], v[2:3]
	v_mov_b64_e32 v[32:33], v[0:1]
	v_mov_b64_e32 v[28:29], v[12:13]
	v_mov_b64_e32 v[26:27], v[10:11]
	v_mov_b64_e32 v[24:25], v[8:9]
	v_mov_b64_e32 v[22:23], v[6:7]
	v_mov_b64_e32 v[20:21], v[4:5]
	v_mov_b64_e32 v[18:19], v[2:3]
	v_mov_b64_e32 v[16:17], v[0:1]
	s_waitcnt vmcnt(1)
	ds_write_b128 v192, v[146:149] offset:34816
	s_waitcnt vmcnt(0)
	ds_write_b128 v193, v[150:153] offset:34816
	s_waitcnt lgkmcnt(0)
	s_barrier
	s_branch .LBB0_465

; #define LAS __attribute__((address_space(3)))
; __device__ __forceinline__ unsigned pk2(float lo, float hi) { f32x2 v = {lo, hi}; bf16x2_t b = __builtin_convertvector(v, bf16x2_t); return __builtin_bit_cast(unsigned, b); }
; __device__ __forceinline__ float bflo(unsigned w) { return __uint_as_float(w << 16); }
; __device__ __forceinline__ float bfhi(unsigned w) { return __uint_as_float(w & 0xffff0000u); }
; __device__ __forceinline__ u32x4 knorm8(u32x4 w, const f32x4 ga, const f32x4 gb) {
;     float v[8];
; #pragma unroll
;     for (int q = 0; q < 4; ++q) { v[2 * q] = bflo(w[q]); v[2 * q + 1] = bfhi(w[q]); }
;     float ss = 0.f;
; #pragma unroll
;     for (int e = 0; e < 8; ++e) ss += v[e] * v[e];
;     ss += __shfl_xor(ss, 1); ss += __shfl_xor(ss, 2); ss += __shfl_xor(ss, 4); ss += __shfl_xor(ss, 8);
;     const float r = __builtin_amdgcn_rsqf(ss * (1.0f / HD) + RMS_EPS);
;     u32x4 o; o.x = pk2(v[0] * r * ga[0], v[1] * r * ga[1]); o.y = pk2(v[2] * r * ga[2], v[3] * r * ga[3]); o.z = pk2(v[4] * r * gb[0], v[5] * r * gb[1]); o.w = pk2(v[6] * r * gb[2], v[7] * r * gb[3]);
;     return o;
; }
; __device__ __forceinline__ void attn_unit(int b, int h, int qb, const bf16_t* __restrict__ QK, const bf16_t* __restrict__ VT, bf16_t* __restrict__ O, const float* __restrict__ qg, const float* __restrict__ kg, ...
;     ...
;         if (kt > 0) { const int nb = buf ^ 1; *(LAS u32x4*)(Kb + nb * AK_BUF + kl0) = knorm8(sk0, kga, kgb); *(LAS u32x4*)(Kb + nb * AK_BUF + kl1) = knorm8(sk1, kga, kgb); *(LAS u32x4*)(Vb + nb * AV_BUF + vl0) = sv0; *(LAS u32x4*)(Vb + nb * AV_BUF + vl1) = sv1; }
.LBB0_472:
	s_or_b64 exec, exec, s[52:53]
	s_andn2_b64 vcc, exec, s[60:61]
	s_cbranch_vccnz .LBB0_474
	s_waitcnt vmcnt(3)
	v_lshlrev_b32_e32 v76, 16, v114
	v_and_b32_e32 v77, 0xffff0000, v114
	v_lshlrev_b32_e32 v72, 16, v115
	v_and_b32_e32 v73, 0xffff0000, v115
	v_pk_mul_f32 v[78:79], v[76:77], v[76:77]
	v_pk_mul_f32 v[74:75], v[72:73], v[72:73]
	v_add_f32_e32 v78, v78, v79
	v_lshlrev_b32_e32 v66, 16, v116
	v_and_b32_e32 v67, 0xffff0000, v116
	v_add_f32_e32 v74, v74, v78
	v_pk_mul_f32 v[70:71], v[66:67], v[66:67]
	v_add_f32_e32 v74, v75, v74
	v_lshlrev_b32_e32 v68, 16, v117
	v_and_b32_e32 v69, 0xffff0000, v117
	v_add_f32_e32 v70, v70, v74
	v_pk_mul_f32 v[64:65], v[68:69], v[68:69]
	v_add_f32_e32 v70, v71, v70
	v_add_f32_e32 v64, v64, v70
	v_add_f32_e32 v64, v65, v64
	s_nop 1
	v_mov_b32_dpp v65, v64 quad_perm:[1,0,3,2] row_mask:0xf bank_mask:0xf
	s_xor_b32 s3, s26, 1
	s_mul_i32 s27, s3, 0x4400
	s_add_i32 s27, s27, 0
	s_lshl_b32 s3, s3, 10
	s_waitcnt lgkmcnt(0)
	v_add_f32_e32 v64, v64, v65
	s_nop 1
	v_mov_b32_dpp v65, v64 quad_perm:[2,3,0,1] row_mask:0xf bank_mask:0xf
	s_waitcnt lgkmcnt(0)
	v_add_f32_e32 v64, v64, v65
	s_nop 1
	v_mov_b32_dpp v65, v64 row_shl:4 row_mask:0xf bank_mask:0x5
	v_mov_b32_dpp v65, v64 row_shr:4 row_mask:0xf bank_mask:0xa
	s_waitcnt lgkmcnt(0)
	v_add_f32_e32 v64, v64, v65
	s_nop 1
	v_mov_b32_dpp v65, v64 row_ror:8 row_mask:0xf bank_mask:0xf
	s_waitcnt lgkmcnt(0)
	v_add_f32_e32 v64, v64, v65
	v_fmamk_f32 v64, v64, 0x3c000000, v243
	v_rsq_f32_e32 v70, v64
	s_nop 0
	v_pk_mul_f32 v[64:65], v[70:71], v[76:77] op_sel_hi:[0,1]
	v_pk_mul_f32 v[72:73], v[70:71], v[72:73] op_sel_hi:[0,1]
	v_pk_mul_f32 v[64:65], v[102:103], v[64:65]
	v_pk_mul_f32 v[72:73], v[104:105], v[72:73]
	v_pk_mul_f32 v[66:67], v[70:71], v[66:67] op_sel_hi:[0,1]
	v_pk_mul_f32 v[68:69], v[70:71], v[68:69] op_sel_hi:[0,1]
	s_waitcnt vmcnt(2)
	v_lshlrev_b32_e32 v76, 16, v130
	v_and_b32_e32 v77, 0xffff0000, v130
	v_cvt_pk_bf16_f32 v64, v64, v65
	v_cvt_pk_bf16_f32 v65, v72, v73
	v_pk_mul_f32 v[66:67], v[98:99], v[66:67]
	v_pk_mul_f32 v[68:69], v[100:101], v[68:69]
	v_lshlrev_b32_e32 v72, 16, v131
	v_and_b32_e32 v73, 0xffff0000, v131
	v_pk_mul_f32 v[78:79], v[76:77], v[76:77]
	v_cvt_pk_bf16_f32 v66, v66, v67
	v_cvt_pk_bf16_f32 v67, v68, v69
	v_add_u32_e32 v68, s27, v164
	v_pk_mul_f32 v[74:75], v[72:73], v[72:73]
	v_add_f32_e32 v78, v78, v79
	ds_write_b128 v68, v[64:67]
	v_lshlrev_b32_e32 v66, 16, v132
	v_and_b32_e32 v67, 0xffff0000, v132
	v_add_f32_e32 v74, v74, v78
	v_pk_mul_f32 v[70:71], v[66:67], v[66:67]
	v_add_f32_e32 v74, v75, v74
	v_lshlrev_b32_e32 v68, 16, v133
	v_and_b32_e32 v69, 0xffff0000, v133
	v_add_f32_e32 v70, v70, v74
	v_pk_mul_f32 v[64:65], v[68:69], v[68:69]
	v_add_f32_e32 v70, v71, v70
	v_add_f32_e32 v64, v64, v70
	v_add_f32_e32 v64, v65, v64
	s_nop 1
	v_mov_b32_dpp v65, v64 quad_perm:[1,0,3,2] row_mask:0xf bank_mask:0xf
	s_waitcnt lgkmcnt(0)
	v_add_f32_e32 v64, v64, v65
	s_nop 1
	v_mov_b32_dpp v65, v64 quad_perm:[2,3,0,1] row_mask:0xf bank_mask:0xf
	s_waitcnt lgkmcnt(0)
	v_add_f32_e32 v64, v64, v65
	s_nop 1
	v_mov_b32_dpp v65, v64 row_shl:4 row_mask:0xf bank_mask:0x5
	v_mov_b32_dpp v65, v64 row_shr:4 row_mask:0xf bank_mask:0xa
	s_waitcnt lgkmcnt(0)
	v_add_f32_e32 v64, v64, v65
	s_nop 1
	v_mov_b32_dpp v65, v64 row_ror:8 row_mask:0xf bank_mask:0xf
	s_waitcnt lgkmcnt(0)
	v_add_f32_e32 v64, v64, v65
	v_fmamk_f32 v64, v64, 0x3c000000, v243
	v_rsq_f32_e32 v70, v64
	s_nop 0
	v_pk_mul_f32 v[64:65], v[70:71], v[76:77] op_sel_hi:[0,1]
	v_pk_mul_f32 v[72:73], v[70:71], v[72:73] op_sel_hi:[0,1]
	v_pk_mul_f32 v[66:67], v[70:71], v[66:67] op_sel_hi:[0,1]
	v_pk_mul_f32 v[68:69], v[70:71], v[68:69] op_sel_hi:[0,1]
	v_pk_mul_f32 v[64:65], v[102:103], v[64:65]
	v_pk_mul_f32 v[72:73], v[104:105], v[72:73]
	v_pk_mul_f32 v[66:67], v[98:99], v[66:67]
	v_pk_mul_f32 v[68:69], v[100:101], v[68:69]
	v_cvt_pk_bf16_f32 v64, v64, v65
	v_cvt_pk_bf16_f32 v65, v72, v73
	v_cvt_pk_bf16_f32 v66, v66, v67
	v_cvt_pk_bf16_f32 v67, v68, v69
	v_add_u32_e32 v68, s27, v156
	s_add_i32 s27, s27, s3
	ds_write_b128 v68, v[64:67]
	v_add_u32_e32 v64, s27, v160
	s_waitcnt vmcnt(1)
	ds_write_b128 v64, v[146:149] offset:34816
	v_add_u32_e32 v64, s27, v166
	s_waitcnt vmcnt(0)
	ds_write_b128 v64, v[150:153] offset:34816

; __device__ __forceinline__ unsigned pk2(float lo, float hi) { f32x2 v = {lo, hi}; bf16x2_t b = __builtin_convertvector(v, bf16x2_t); return __builtin_bit_cast(unsigned, b); }
; __device__ __forceinline__ void attn_unit(int b, int h, int qb, const bf16_t* __restrict__ QK, const bf16_t* __restrict__ VT, bf16_t* __restrict__ O, const float* __restrict__ qg, const float* __restrict__ kg, ...
;     ...
;     bf16_t* op = O + (size_t)(b * SEQ + q0 + wid * 32) * DM + h * HD + r32;
; #pragma unroll
;     for (int r = 0; r < 16; ++r) { const int qrow = (r & 3) + 8 * (r >> 2) + 4 * hi;
; #pragma unroll
;         for (int d = 0; d < 4; ++d) op[(size_t)qrow * DM + d * 32] = (bf16_t)(pk2(o[d][r], 0.f) & 0xffffu); }
.LBB0_476:
	s_bfe_u32 s13, s55, 0x20008
	s_lshl_b32 s16, s13, 2
	s_or_b32 s34, s16, 2
	s_add_i32 s16, s23, s12
	s_lshl_b32 s3, s13, 8
	s_lshl_b32 s13, s13, 5
	s_ashr_i32 s17, s16, 31
	s_bitset1_b32 s3, 7
	s_or_b32 s13, s13, 24
	s_lshl_b64 s[16:17], s[16:17], 12
	s_add_u32 s16, s41, s16
	s_addc_u32 s17, s46, s17
	s_add_u32 s16, s16, s14
	s_addc_u32 s17, s17, s15
	v_mov_b32_e32 v175, v97
	v_lshl_add_u64 v[64:65], s[16:17], 0, v[174:175]
	v_mov_b32_e32 v173, v97
	v_cvt_pk_bf16_f32 v0, v0, s0
	v_lshl_add_u64 v[64:65], v[64:65], 0, v[172:173]
	global_store_short v[64:65], v0, off
	v_cvt_pk_bf16_f32 v0, v48, s0
	global_store_short v[64:65], v0, off offset:64
	v_cvt_pk_bf16_f32 v0, v32, s0
	global_store_short v[64:65], v0, off offset:128
	v_cvt_pk_bf16_f32 v0, v16, s0
	global_store_short v[64:65], v0, off offset:192
	v_add_co_u32_e32 v0, vcc, s74, v64
	v_cvt_pk_bf16_f32 v16, v1, s0
	s_nop 0
	v_addc_co_u32_e32 v1, vcc, 0, v65, vcc
	v_add_co_u32_e32 v66, vcc, s81, v64
	s_movk_i32 s16, 0x3000
	s_nop 0
	v_addc_co_u32_e32 v67, vcc, 0, v65, vcc
	global_store_short v[66:67], v16, off offset:-4096
	v_cvt_pk_bf16_f32 v16, v49, s0
	global_store_short v[0:1], v16, off offset:64
	v_cvt_pk_bf16_f32 v16, v33, s0
	global_store_short v[0:1], v16, off offset:128
	v_cvt_pk_bf16_f32 v16, v17, s0
	global_store_short v[0:1], v16, off offset:192
	v_cvt_pk_bf16_f32 v0, v2, s0
	global_store_short v[66:67], v0, off
	v_cvt_pk_bf16_f32 v0, v50, s0
	global_store_short v[66:67], v0, off offset:64
	v_cvt_pk_bf16_f32 v0, v34, s0
	global_store_short v[66:67], v0, off offset:128
	v_cvt_pk_bf16_f32 v0, v18, s0
	global_store_short v[66:67], v0, off offset:192
	v_add_co_u32_e32 v0, vcc, s16, v64
	v_cvt_pk_bf16_f32 v2, v3, s0
	s_nop 0
	v_addc_co_u32_e32 v1, vcc, 0, v65, vcc
	global_store_short v[0:1], v2, off
	v_cvt_pk_bf16_f32 v2, v51, s0
	global_store_short v[0:1], v2, off offset:64
	v_cvt_pk_bf16_f32 v2, v35, s0
	global_store_short v[0:1], v2, off offset:128
	v_cvt_pk_bf16_f32 v2, v19, s0
	s_mov_b32 s16, 0x8000
	global_store_short v[0:1], v2, off offset:192
	v_add_co_u32_e32 v0, vcc, s16, v64
	s_mov_b32 s16, 0x9000
	s_nop 0
	v_addc_co_u32_e32 v1, vcc, 0, v65, vcc
	v_add_co_u32_e32 v2, vcc, s16, v64
	v_cvt_pk_bf16_f32 v4, v4, s0
	s_nop 0
	v_addc_co_u32_e32 v3, vcc, 0, v65, vcc
	global_store_short v[2:3], v4, off offset:-4096
	v_cvt_pk_bf16_f32 v4, v52, s0
	global_store_short v[0:1], v4, off offset:64
	v_cvt_pk_bf16_f32 v4, v36, s0
	global_store_short v[0:1], v4, off offset:128
	v_cvt_pk_bf16_f32 v4, v20, s0
	global_store_short v[0:1], v4, off offset:192
	v_cvt_pk_bf16_f32 v0, v5, s0
	global_store_short v[2:3], v0, off
	v_cvt_pk_bf16_f32 v0, v53, s0
	global_store_short v[2:3], v0, off offset:64
	v_cvt_pk_bf16_f32 v0, v37, s0
	global_store_short v[2:3], v0, off offset:128
	v_cvt_pk_bf16_f32 v0, v21, s0
	s_mov_b32 s16, 0xa000
	global_store_short v[2:3], v0, off offset:192
	v_add_co_u32_e32 v0, vcc, s16, v64
	v_cvt_pk_bf16_f32 v4, v6, s0
	s_nop 0
	v_addc_co_u32_e32 v1, vcc, 0, v65, vcc
	v_add_co_u32_e32 v2, vcc, s49, v64
	s_mov_b32 s16, 0x10000
	s_nop 0
	v_addc_co_u32_e32 v3, vcc, 0, v65, vcc
	global_store_short v[2:3], v4, off offset:-4096
	v_cvt_pk_bf16_f32 v4, v54, s0
	global_store_short v[0:1], v4, off offset:64
	v_cvt_pk_bf16_f32 v4, v38, s0
	global_store_short v[0:1], v4, off offset:128
	v_cvt_pk_bf16_f32 v4, v22, s0
	global_store_short v[0:1], v4, off offset:192
	v_cvt_pk_bf16_f32 v0, v7, s0
	global_store_short v[2:3], v0, off
	v_cvt_pk_bf16_f32 v0, v55, s0
	global_store_short v[2:3], v0, off offset:64
	v_cvt_pk_bf16_f32 v0, v39, s0
	global_store_short v[2:3], v0, off offset:128
	v_cvt_pk_bf16_f32 v0, v23, s0
	global_store_short v[2:3], v0, off offset:192
	v_add_co_u32_e32 v0, vcc, s16, v64
	s_mov_b32 s16, 0x11000
	s_nop 0
	v_addc_co_u32_e32 v1, vcc, 0, v65, vcc
	v_add_co_u32_e32 v2, vcc, s16, v64
	v_cvt_pk_bf16_f32 v4, v8, s0
	s_nop 0
	v_addc_co_u32_e32 v3, vcc, 0, v65, vcc
	global_store_short v[2:3], v4, off offset:-4096
	v_cvt_pk_bf16_f32 v4, v56, s0
	global_store_short v[0:1], v4, off offset:64
	v_cvt_pk_bf16_f32 v4, v40, s0
	global_store_short v[0:1], v4, off offset:128
	v_cvt_pk_bf16_f32 v4, v24, s0
	global_store_short v[0:1], v4, off offset:192
	v_cvt_pk_bf16_f32 v0, v9, s0
	global_store_short v[2:3], v0, off
	v_cvt_pk_bf16_f32 v0, v57, s0
	global_store_short v[2:3], v0, off offset:64
	v_cvt_pk_bf16_f32 v0, v41, s0
	global_store_short v[2:3], v0, off offset:128
	v_cvt_pk_bf16_f32 v0, v25, s0
	global_store_short v[2:3], v0, off offset:192
	v_add_co_u32_e32 v0, vcc, s80, v64
	s_mov_b32 s16, 0x13000
	s_nop 0
	v_addc_co_u32_e32 v1, vcc, 0, v65, vcc
	v_add_co_u32_e32 v2, vcc, s16, v64
	v_cvt_pk_bf16_f32 v4, v10, s0
	s_nop 0
	v_addc_co_u32_e32 v3, vcc, 0, v65, vcc
	global_store_short v[2:3], v4, off offset:-4096
	v_cvt_pk_bf16_f32 v4, v58, s0
	global_store_short v[0:1], v4, off offset:64
	v_cvt_pk_bf16_f32 v4, v42, s0
	global_store_short v[0:1], v4, off offset:128
	v_cvt_pk_bf16_f32 v4, v26, s0
	global_store_short v[0:1], v4, off offset:192
	v_cvt_pk_bf16_f32 v0, v11, s0
	global_store_short v[2:3], v0, off
	v_cvt_pk_bf16_f32 v0, v59, s0
	global_store_short v[2:3], v0, off offset:64
	v_cvt_pk_bf16_f32 v0, v43, s0
	global_store_short v[2:3], v0, off offset:128
	v_cvt_pk_bf16_f32 v0, v27, s0
	s_mov_b32 s16, 0x18000
	global_store_short v[2:3], v0, off offset:192
	v_add_co_u32_e32 v0, vcc, s16, v64
	s_mov_b32 s16, 0x19000
	s_nop 0
	v_addc_co_u32_e32 v1, vcc, 0, v65, vcc
	v_add_co_u32_e32 v2, vcc, s16, v64
	v_cvt_pk_bf16_f32 v4, v12, s0
	s_nop 0
	v_addc_co_u32_e32 v3, vcc, 0, v65, vcc
	global_store_short v[2:3], v4, off offset:-4096
	v_cvt_pk_bf16_f32 v4, v60, s0
; #define LAS __attribute__((address_space(3)))
; __device__ __forceinline__ unsigned pk2(float lo, float hi) { f32x2 v = {lo, hi}; bf16x2_t b = __builtin_convertvector(v, bf16x2_t); return __builtin_bit_cast(unsigned, b); }
; __device__ __forceinline__ float bflo(unsigned w) { return __uint_as_float(w << 16); }
; __device__ __forceinline__ float bfhi(unsigned w) { return __uint_as_float(w & 0xffff0000u); }
; __device__ __forceinline__ void attn_unit(int b, int h, int qb, const bf16_t* __restrict__ QK, const bf16_t* __restrict__ VT, bf16_t* __restrict__ O, const float* __restrict__ qg, const float* __restrict__ kg, ...
;     const int r32 = lane & 31, hi = lane >> 5;
;     const int q0 = qb * 256, NT = (q0 + 256) / 64;
;     LAS unsigned char* Kb = lds; LAS unsigned char* Vb = lds + 2 * AK_BUF;
;     LAS unsigned* flags = (LAS unsigned*)(lds + 2 * AK_BUF + 2 * AV_BUF);
;     const int kc0 = tid, kc1 = tid + 512;
;     const bf16_t* kg0 = QK + (size_t)(b * SEQ + (kc0 >> 4)) * 4096 + 2048 + h * HD + (kc0 & 15) * 8;
;     const bf16_t* kg1 = QK + (size_t)(b * SEQ + (kc1 >> 4)) * 4096 + 2048 + h * HD + (kc1 & 15) * 8;
;     const bf16_t* vg0 = VT + (size_t)(h * HD + (kc0 >> 3)) * MTOK + b * SEQ + (kc0 & 7) * 8;
;     const bf16_t* vg1 = VT + (size_t)(h * HD + (kc1 >> 3)) * MTOK + b * SEQ + (kc1 & 7) * 8;
;     const int kl0 = (kc0 >> 4) * AK_ROWB + (kc0 & 15) * 16, kl1 = (kc1 >> 4) * AK_ROWB + (kc1 & 15) * 16;
;     const int vl0 = (kc0 >> 3) * AV_ROWB + (kc0 & 7) * 16, vl1 = (kc1 >> 3) * AV_ROWB + (kc1 & 7) * 16;
;     const f32x4 kga = *(const f32x4*)(kg + (tid & 15) * 8), kgb = *(const f32x4*)(kg + (tid & 15) * 8 + 4);
;     const int tq = q0 + wid * 32 + r32;
;     bf16x8 qr[8];
;     { const bf16_t* qp = QK + (size_t)(b * SEQ + tq) * 4096 + h * HD + hi * 8;
;       u32x4 raw[8]; float ss = 0.f;
; #pragma unroll
;       for (int ks = 0; ks < 8; ++ks) { raw[ks] = *(const u32x4*)(qp + ks * 16);
; #pragma unroll
;           for (int q = 0; q < 4; ++q) { const float a = bflo(raw[ks][q]), c = bfhi(raw[ks][q]); ss += a * a + c * c; } }
;     ...
;     bf16_t* op = O + (size_t)(b * SEQ + q0 + wid * 32) * DM + h * HD + r32;
; #pragma unroll
;     for (int r = 0; r < 16; ++r) { const int qrow = (r & 3) + 8 * (r >> 2) + 4 * hi;
; #pragma unroll
;         for (int d = 0; d < 4; ++d) op[(size_t)qrow * DM + d * 32] = (bf16_t)(pk2(o[d][r], 0.f) & 0xffffu); }
	global_store_short v[0:1], v4, off offset:64
	v_cvt_pk_bf16_f32 v4, v44, s0
	global_store_short v[0:1], v4, off offset:128
	v_cvt_pk_bf16_f32 v4, v28, s0
	global_store_short v[0:1], v4, off offset:192
	v_cvt_pk_bf16_f32 v0, v13, s0
	global_store_short v[2:3], v0, off
	v_cvt_pk_bf16_f32 v0, v61, s0
	global_store_short v[2:3], v0, off offset:64
	v_cvt_pk_bf16_f32 v0, v45, s0
	global_store_short v[2:3], v0, off offset:128
	v_cvt_pk_bf16_f32 v0, v29, s0
	s_mov_b32 s16, 0x1a000
	global_store_short v[2:3], v0, off offset:192
	v_add_co_u32_e32 v0, vcc, s16, v64
	s_mov_b32 s16, 0x1b000
	s_nop 0
	v_addc_co_u32_e32 v1, vcc, 0, v65, vcc
	v_add_co_u32_e32 v2, vcc, s16, v64
	v_cvt_pk_bf16_f32 v4, v14, s0
	s_nop 0
	v_addc_co_u32_e32 v3, vcc, 0, v65, vcc
	global_store_short v[2:3], v4, off offset:-4096
	v_cvt_pk_bf16_f32 v4, v62, s0
	global_store_short v[0:1], v4, off offset:64
	v_cvt_pk_bf16_f32 v4, v46, s0
	global_store_short v[0:1], v4, off offset:128
	v_cvt_pk_bf16_f32 v4, v30, s0
	global_store_short v[0:1], v4, off offset:192
	v_cvt_pk_bf16_f32 v0, v15, s0
	global_store_short v[2:3], v0, off
	v_cvt_pk_bf16_f32 v0, v63, s0
	global_store_short v[2:3], v0, off offset:64
	v_cvt_pk_bf16_f32 v0, v47, s0
	s_add_i32 s23, s2, s47
	global_store_short v[2:3], v0, off offset:128
	v_cvt_pk_bf16_f32 v0, v31, s0
	v_or_b32_e32 v173, s23, v154
	global_store_short v[2:3], v0, off offset:192
	v_add_u32_e32 v0, s12, v173
	v_ashrrev_i32_e32 v1, 31, v0
	v_lshlrev_b64 v[0:1], 13, v[0:1]
	v_lshl_add_u64 v[0:1], s[8:9], 0, v[0:1]
	v_lshl_add_u64 v[0:1], v[0:1], 0, s[14:15]
	v_mov_b32_e32 v169, v97
	v_lshl_add_u64 v[0:1], v[0:1], 0, v[168:169]
	s_waitcnt vmcnt(63) expcnt(7) lgkmcnt(15)
	s_barrier
	global_load_dwordx4 v[36:39], v[0:1], off offset:224
	global_load_dwordx4 v[40:43], v[0:1], off offset:192
	global_load_dwordx4 v[44:47], v[0:1], off offset:160
	global_load_dwordx4 v[84:87], v[0:1], off offset:128
	global_load_dwordx4 v[98:101], v[0:1], off offset:96
	global_load_dwordx4 v[102:105], v[0:1], off offset:64
	global_load_dwordx4 v[106:109], v[0:1], off
	global_load_dwordx4 v[114:117], v[0:1], off offset:32
	global_load_dwordx4 v[32:35], v[162:163], off offset:16
	global_load_dwordx4 v[48:51], v[162:163], off
	global_load_dwordx4 v[24:27], v[162:163], off offset:80
	global_load_dwordx4 v[28:31], v[162:163], off offset:64
	global_load_dwordx4 v[16:19], v[162:163], off offset:144
	global_load_dwordx4 v[20:23], v[162:163], off offset:128
	global_load_dwordx4 v[8:11], v[162:163], off offset:208
	global_load_dwordx4 v[12:15], v[162:163], off offset:192
	global_load_dwordx4 v[0:3], v[162:163], off offset:272
	global_load_dwordx4 v[4:7], v[162:163], off offset:256
	s_addk_i32 s2, 0x100
	s_lshr_b32 s2, s2, 6
	s_add_i32 s18, s2, -1
	s_lshl_b64 s[16:17], s[18:19], 19
	s_lshl_b32 s18, s18, 7
	s_mov_b32 s24, 0
	s_or_b32 s2, s23, 31
	s_waitcnt vmcnt(11)
	v_lshlrev_b32_e32 v198, 16, v107
	v_and_b32_e32 v199, 0xffff0000, v107
	v_lshlrev_b32_e32 v210, 16, v106
	v_and_b32_e32 v211, 0xffff0000, v106
	v_lshlrev_b32_e32 v196, 16, v108
	v_and_b32_e32 v197, 0xffff0000, v108
	v_pk_mul_f32 v[200:201], v[198:199], v[198:199]
	v_pk_mul_f32 v[106:107], v[210:211], v[210:211]
	v_lshlrev_b32_e32 v128, 16, v109
	v_and_b32_e32 v129, 0xffff0000, v109
	v_pk_mul_f32 v[108:109], v[196:197], v[196:197]
	v_add_f32_e32 v175, v200, v201
	v_add_f32_e32 v106, v106, v107
	s_waitcnt vmcnt(10)
	v_lshlrev_b32_e32 v110, 16, v114
	v_and_b32_e32 v111, 0xffff0000, v114
	v_pk_mul_f32 v[194:195], v[128:129], v[128:129]
	v_add_f32_e32 v106, v106, v175
	v_add_f32_e32 v107, v108, v109
	v_lshlrev_b32_e32 v126, 16, v115
	v_and_b32_e32 v127, 0xffff0000, v115
	v_pk_mul_f32 v[114:115], v[110:111], v[110:111]
	v_add_f32_e32 v169, v194, v195
	v_add_f32_e32 v106, v107, v106
	v_lshlrev_b32_e32 v112, 16, v116
	v_and_b32_e32 v113, 0xffff0000, v116
	v_pk_mul_f32 v[152:153], v[126:127], v[126:127]
	v_add_f32_e32 v106, v169, v106
	v_add_f32_e32 v107, v114, v115
	v_lshlrev_b32_e32 v124, 16, v117
	v_and_b32_e32 v125, 0xffff0000, v117
	v_pk_mul_f32 v[116:117], v[112:113], v[112:113]
	v_add_f32_e32 v106, v107, v106
	v_add_f32_e32 v107, v152, v153
	v_lshlrev_b32_e32 v118, 16, v102
	v_and_b32_e32 v119, 0xffff0000, v102
	v_pk_mul_f32 v[150:151], v[124:125], v[124:125]
	v_add_f32_e32 v106, v107, v106
	v_add_f32_e32 v107, v116, v117
	v_lshlrev_b32_e32 v122, 16, v103
	v_and_b32_e32 v123, 0xffff0000, v103
	v_pk_mul_f32 v[102:103], v[118:119], v[118:119]
	v_add_f32_e32 v106, v107, v106
	v_add_f32_e32 v107, v150, v151
	v_lshlrev_b32_e32 v120, 16, v104
	v_and_b32_e32 v121, 0xffff0000, v104
	v_pk_mul_f32 v[148:149], v[122:123], v[122:123]
	v_add_f32_e32 v106, v107, v106
	v_add_f32_e32 v102, v102, v103
	v_lshlrev_b32_e32 v94, 16, v105
	v_and_b32_e32 v95, 0xffff0000, v105
	v_pk_mul_f32 v[104:105], v[120:121], v[120:121]
	v_add_f32_e32 v102, v102, v106
	v_add_f32_e32 v103, v148, v149
	v_lshlrev_b32_e32 v92, 16, v98
	v_and_b32_e32 v93, 0xffff0000, v98
	v_pk_mul_f32 v[146:147], v[94:95], v[94:95]
	v_add_f32_e32 v102, v103, v102
	v_add_f32_e32 v103, v104, v105
	v_lshlrev_b32_e32 v90, 16, v99
	v_and_b32_e32 v91, 0xffff0000, v99
	v_pk_mul_f32 v[98:99], v[92:93], v[92:93]
	v_add_f32_e32 v102, v103, v102
	v_add_f32_e32 v103, v146, v147
	v_lshlrev_b32_e32 v88, 16, v100
	v_and_b32_e32 v89, 0xffff0000, v100
	v_pk_mul_f32 v[144:145], v[90:91], v[90:91]
	v_add_f32_e32 v102, v103, v102
	v_add_f32_e32 v98, v98, v99
	v_lshlrev_b32_e32 v80, 16, v85
	v_and_b32_e32 v81, 0xffff0000, v85
	v_lshlrev_b32_e32 v82, 16, v84
	v_and_b32_e32 v83, 0xffff0000, v84
	v_lshlrev_b32_e32 v84, 16, v101
	v_and_b32_e32 v85, 0xffff0000, v101
	v_pk_mul_f32 v[100:101], v[88:89], v[88:89]
; __device__ __forceinline__ unsigned pk2(float lo, float hi) { f32x2 v = {lo, hi}; bf16x2_t b = __builtin_convertvector(v, bf16x2_t); return __builtin_bit_cast(unsigned, b); }
; __device__ __forceinline__ float bflo(unsigned w) { return __uint_as_float(w << 16); }
; __device__ __forceinline__ float bfhi(unsigned w) { return __uint_as_float(w & 0xffff0000u); }
; __device__ __forceinline__ void attn_unit(int b, int h, int qb, const bf16_t* __restrict__ QK, const bf16_t* __restrict__ VT, bf16_t* __restrict__ O, const float* __restrict__ qg, const float* __restrict__ kg, ...
;     ...
;           for (int q = 0; q < 4; ++q) { const float a = bflo(raw[ks][q]), c = bfhi(raw[ks][q]); ss += a * a + c * c; } }
;       ss += __shfl_xor(ss, 32);
;       const float r = __builtin_amdgcn_rsqf(ss * (1.0f / HD) + RMS_EPS) * (1.4426950408889634f * 0.08838834764831845f);
; #pragma unroll
;       for (int ks = 0; ks < 8; ++ks) { const f32x4 ga = *(const f32x4*)(qg + ks * 16 + hi * 8), gb = *(const f32x4*)(qg + ks * 16 + hi * 8 + 4); u32x4 o;
;           o.x = pk2(bflo(raw[ks][0]) * r * ga[0], bfhi(raw[ks][0]) * r * ga[1]); o.y = pk2(bflo(raw[ks][1]) * r * ga[2], bfhi(raw[ks][1]) * r * ga[3]);
;           o.z = pk2(bflo(raw[ks][2]) * r * gb[0], bfhi(raw[ks][2]) * r * gb[1]); o.w = pk2(bflo(raw[ks][3]) * r * gb[2], bfhi(raw[ks][3]) * r * gb[3]);
;           qr[ks] = __builtin_bit_cast(bf16x8, o); } }
;     const int krow = 16 * ((r32 >> 2) & 1) + (r32 & 3) + 4 * (r32 >> 3);
;     const int kfo = krow * AK_ROWB + hi * 16, vfo = r32 * AV_ROWB + hi * 32;
;     f32x16 o[4];
; #pragma unroll
;     for (int d = 0; d < 4; ++d)
; #pragma unroll
;         for (int r = 0; r < 16; ++r) o[d][r] = 0.f;
;     float R = 0.f; bool wdone = false;
;     u32x4 sk0, sk1, sv0, sv1;
;     { const int kt = NT - 1; sk0 = *(const u32x4*)(kg0 + (size_t)kt * 64 * 4096); sk1 = *(const u32x4*)(kg1 + (size_t)kt * 64 * 4096); sv0 = *(const u32x4*)(vg0 + kt * 64); sv1 = *(const u32x4*)(vg1 + kt * 64); }
	v_add_f32_e32 v98, v98, v102
	v_add_f32_e32 v99, v144, v145
	v_and_b32_e32 v53, 0xffff0000, v39
	v_and_b32_e32 v55, 0xffff0000, v38
	v_pk_mul_f32 v[142:143], v[84:85], v[84:85]
	v_add_f32_e32 v98, v99, v98
	v_add_f32_e32 v99, v100, v101
	v_lshlrev_b32_e32 v52, 16, v39
	v_lshlrev_b32_e32 v54, 16, v38
	v_mov_b32_e32 v56, v53
	v_mov_b32_e32 v57, v55
	v_pk_mul_f32 v[140:141], v[82:83], v[82:83]
	v_add_f32_e32 v98, v99, v98
	v_add_f32_e32 v99, v142, v143
	v_mov_b32_e32 v38, v52
	v_mov_b32_e32 v39, v54
	v_pk_mul_f32 v[56:57], v[56:57], v[56:57]
	v_lshlrev_b32_e32 v78, 16, v86
	v_and_b32_e32 v79, 0xffff0000, v86
	v_pk_mul_f32 v[138:139], v[80:81], v[80:81]
	v_add_f32_e32 v98, v99, v98
	v_add_f32_e32 v99, v140, v141
	v_pk_fma_f32 v[38:39], v[38:39], v[38:39], v[56:57]
	v_and_b32_e32 v57, 0xffff0000, v37
	v_and_b32_e32 v59, 0xffff0000, v36
	v_lshlrev_b32_e32 v76, 16, v87
	v_and_b32_e32 v77, 0xffff0000, v87
	v_pk_mul_f32 v[86:87], v[78:79], v[78:79]
	v_add_f32_e32 v98, v99, v98
	v_add_f32_e32 v99, v138, v139
	v_lshlrev_b32_e32 v56, 16, v37
	v_lshlrev_b32_e32 v58, 16, v36
	v_mov_b32_e32 v60, v57
	v_mov_b32_e32 v61, v59
	v_lshlrev_b32_e32 v74, 16, v44
	v_and_b32_e32 v75, 0xffff0000, v44
	v_pk_mul_f32 v[136:137], v[76:77], v[76:77]
	v_add_f32_e32 v98, v99, v98
	v_add_f32_e32 v86, v86, v87
	v_mov_b32_e32 v36, v56
	v_mov_b32_e32 v37, v58
	v_pk_mul_f32 v[60:61], v[60:61], v[60:61]
	v_lshlrev_b32_e32 v72, 16, v45
	v_and_b32_e32 v73, 0xffff0000, v45
	v_pk_mul_f32 v[44:45], v[74:75], v[74:75]
	v_add_f32_e32 v86, v86, v98
	v_add_f32_e32 v87, v136, v137
	v_pk_fma_f32 v[36:37], v[36:37], v[36:37], v[60:61]
	v_and_b32_e32 v61, 0xffff0000, v43
	v_and_b32_e32 v63, 0xffff0000, v42
	v_lshlrev_b32_e32 v70, 16, v46
	v_and_b32_e32 v71, 0xffff0000, v46
	v_pk_mul_f32 v[134:135], v[72:73], v[72:73]
	v_add_f32_e32 v86, v87, v86
	v_add_f32_e32 v44, v44, v45
	v_lshlrev_b32_e32 v60, 16, v43
	v_lshlrev_b32_e32 v62, 16, v42
	v_mov_b32_e32 v64, v61
	v_mov_b32_e32 v65, v63
	v_lshlrev_b32_e32 v68, 16, v47
	v_and_b32_e32 v69, 0xffff0000, v47
	v_pk_mul_f32 v[46:47], v[70:71], v[70:71]
	v_add_f32_e32 v44, v44, v86
	v_add_f32_e32 v45, v134, v135
	v_mov_b32_e32 v42, v60
	v_mov_b32_e32 v43, v62
	v_pk_mul_f32 v[64:65], v[64:65], v[64:65]
	v_lshlrev_b32_e32 v66, 16, v40
	v_and_b32_e32 v67, 0xffff0000, v40
	v_pk_mul_f32 v[132:133], v[68:69], v[68:69]
	v_add_f32_e32 v44, v45, v44
	v_add_f32_e32 v45, v46, v47
	v_pk_fma_f32 v[42:43], v[42:43], v[42:43], v[64:65]
	v_lshlrev_b32_e32 v64, 16, v41
	v_and_b32_e32 v65, 0xffff0000, v41
	v_pk_mul_f32 v[40:41], v[66:67], v[66:67]
	v_add_f32_e32 v44, v45, v44
	v_add_f32_e32 v45, v132, v133
	v_pk_mul_f32 v[130:131], v[64:65], v[64:65]
	v_add_f32_e32 v44, v45, v44
	v_add_f32_e32 v40, v40, v41
	v_add_f32_e32 v40, v40, v44
	v_add_f32_e32 v41, v130, v131
	v_add_f32_e32 v40, v41, v40
	v_add_f32_e32 v40, v43, v40
	v_add_f32_e32 v40, v42, v40
	v_add_f32_e32 v37, v37, v40
	v_add_f32_e32 v36, v36, v37
	global_load_dwordx4 v[136:139], v[162:163], off offset:336
	global_load_dwordx4 v[140:143], v[162:163], off offset:320
	v_add_f32_e32 v36, v39, v36
	v_add_f32_e32 v36, v38, v36
	ds_bpermute_b32 v37, v157, v36
	global_load_dwordx4 v[98:101], v[158:159], off offset:16
	global_load_dwordx4 v[102:105], v[158:159], off
	v_mov_b32_e32 v169, 0
	s_waitcnt lgkmcnt(0)
	v_add_f32_e32 v36, v36, v37
	v_fmamk_f32 v36, v36, 0x3c000000, v243
	v_rsq_f32_e32 v86, v36
	global_load_dwordx4 v[44:47], v[162:163], off offset:400
	global_load_dwordx4 v[144:147], v[162:163], off offset:384
	global_load_dwordx4 v[36:39], v[162:163], off offset:464
	global_load_dwordx4 v[40:43], v[162:163], off offset:448
	v_mul_f32_e32 v86, 0x3e0293ee, v86
	v_pk_mul_f32 v[106:107], v[86:87], v[210:211] op_sel_hi:[0,1]
	s_waitcnt vmcnt(16)
	v_pk_mul_f32 v[48:49], v[48:49], v[106:107]
	s_nop 0
	v_cvt_pk_bf16_f32 v106, v48, v49
	v_pk_mul_f32 v[48:49], v[86:87], v[198:199] op_sel_hi:[0,1]
	v_pk_mul_f32 v[48:49], v[50:51], v[48:49]
	s_nop 0
	v_cvt_pk_bf16_f32 v107, v48, v49
	v_pk_mul_f32 v[48:49], v[86:87], v[196:197] op_sel_hi:[0,1]
	v_pk_mul_f32 v[32:33], v[32:33], v[48:49]
	v_lshl_add_u64 v[48:49], v[178:179], 0, s[16:17]
	v_cvt_pk_bf16_f32 v108, v32, v33
	v_pk_mul_f32 v[32:33], v[86:87], v[128:129] op_sel_hi:[0,1]
	v_pk_mul_f32 v[32:33], v[34:35], v[32:33]
	global_load_dwordx4 v[114:117], v[48:49], off
	v_cvt_pk_bf16_f32 v109, v32, v33
	v_pk_mul_f32 v[32:33], v[86:87], v[110:111] op_sel_hi:[0,1]
	s_waitcnt vmcnt(15)
	v_pk_mul_f32 v[28:29], v[28:29], v[32:33]
	s_nop 0
	v_cvt_pk_bf16_f32 v110, v28, v29
	v_pk_mul_f32 v[28:29], v[86:87], v[126:127] op_sel_hi:[0,1]
	v_pk_mul_f32 v[28:29], v[30:31], v[28:29]
	s_nop 0
	v_cvt_pk_bf16_f32 v111, v28, v29
	v_pk_mul_f32 v[28:29], v[86:87], v[112:113] op_sel_hi:[0,1]
	v_pk_mul_f32 v[24:25], v[24:25], v[28:29]
	s_nop 0
	v_cvt_pk_bf16_f32 v112, v24, v25
	v_pk_mul_f32 v[24:25], v[86:87], v[124:125] op_sel_hi:[0,1]
	v_pk_mul_f32 v[24:25], v[26:27], v[24:25]
	s_nop 0
	v_cvt_pk_bf16_f32 v113, v24, v25
	v_pk_mul_f32 v[24:25], v[86:87], v[118:119] op_sel_hi:[0,1]
	s_waitcnt vmcnt(13)
	v_pk_mul_f32 v[20:21], v[20:21], v[24:25]
	s_nop 0
	v_cvt_pk_bf16_f32 v118, v20, v21
	v_pk_mul_f32 v[20:21], v[86:87], v[122:123] op_sel_hi:[0,1]
	v_pk_mul_f32 v[20:21], v[22:23], v[20:21]
	s_nop 0
	v_cvt_pk_bf16_f32 v119, v20, v21
	v_pk_mul_f32 v[20:21], v[86:87], v[120:121] op_sel_hi:[0,1]
	v_pk_mul_f32 v[16:17], v[16:17], v[20:21]
	s_nop 0
	v_cvt_pk_bf16_f32 v120, v16, v17
	v_pk_mul_f32 v[16:17], v[86:87], v[94:95] op_sel_hi:[0,1]
	v_pk_mul_f32 v[16:17], v[18:19], v[16:17]
	s_nop 0
	v_cvt_pk_bf16_f32 v121, v16, v17
	v_pk_mul_f32 v[16:17], v[86:87], v[92:93] op_sel_hi:[0,1]
	s_waitcnt vmcnt(11)
; #define LAS __attribute__((address_space(3)))
; __device__ __forceinline__ unsigned pk2(float lo, float hi) { f32x2 v = {lo, hi}; bf16x2_t b = __builtin_convertvector(v, bf16x2_t); return __builtin_bit_cast(unsigned, b); }
; __device__ __forceinline__ u32x4 knorm8(u32x4 w, const f32x4 ga, const f32x4 gb) {
;     float v[8];
; #pragma unroll
;     for (int q = 0; q < 4; ++q) { v[2 * q] = bflo(w[q]); v[2 * q + 1] = bfhi(w[q]); }
;     float ss = 0.f;
; #pragma unroll
;     for (int e = 0; e < 8; ++e) ss += v[e] * v[e];
;     ss += __shfl_xor(ss, 1); ss += __shfl_xor(ss, 2); ss += __shfl_xor(ss, 4); ss += __shfl_xor(ss, 8);
;     const float r = __builtin_amdgcn_rsqf(ss * (1.0f / HD) + RMS_EPS);
;     u32x4 o; o.x = pk2(v[0] * r * ga[0], v[1] * r * ga[1]); o.y = pk2(v[2] * r * ga[2], v[3] * r * ga[3]); o.z = pk2(v[4] * r * gb[0], v[5] * r * gb[1]); o.w = pk2(v[6] * r * gb[2], v[7] * r * gb[3]);
; __device__ __forceinline__ void attn_unit(int b, int h, int qb, const bf16_t* __restrict__ QK, const bf16_t* __restrict__ VT, bf16_t* __restrict__ O, const float* __restrict__ qg, const float* __restrict__ kg, ...
;     ...
;       for (int ks = 0; ks < 8; ++ks) { const f32x4 ga = *(const f32x4*)(qg + ks * 16 + hi * 8), gb = *(const f32x4*)(qg + ks * 16 + hi * 8 + 4); u32x4 o;
;           o.x = pk2(bflo(raw[ks][0]) * r * ga[0], bfhi(raw[ks][0]) * r * ga[1]); o.y = pk2(bflo(raw[ks][1]) * r * ga[2], bfhi(raw[ks][1]) * r * ga[3]);
;           o.z = pk2(bflo(raw[ks][2]) * r * gb[0], bfhi(raw[ks][2]) * r * gb[1]); o.w = pk2(bflo(raw[ks][3]) * r * gb[2], bfhi(raw[ks][3]) * r * gb[3]);
;           qr[ks] = __builtin_bit_cast(bf16x8, o); } }
;     const int krow = 16 * ((r32 >> 2) & 1) + (r32 & 3) + 4 * (r32 >> 3);
;     const int kfo = krow * AK_ROWB + hi * 16, vfo = r32 * AV_ROWB + hi * 32;
;     f32x16 o[4];
; #pragma unroll
;     for (int d = 0; d < 4; ++d)
; #pragma unroll
;         for (int r = 0; r < 16; ++r) o[d][r] = 0.f;
;     float R = 0.f; bool wdone = false;
;     u32x4 sk0, sk1, sv0, sv1;
;     { const int kt = NT - 1; sk0 = *(const u32x4*)(kg0 + (size_t)kt * 64 * 4096); sk1 = *(const u32x4*)(kg1 + (size_t)kt * 64 * 4096); sv0 = *(const u32x4*)(vg0 + kt * 64); sv1 = *(const u32x4*)(vg1 + kt * 64); }
;     *(LAS u32x4*)(Kb + kl0) = knorm8(sk0, kga, kgb); *(LAS u32x4*)(Kb + kl1) = knorm8(sk1, kga, kgb); *(LAS u32x4*)(Vb + vl0) = sv0; *(LAS u32x4*)(Vb + vl1) = sv1;
	v_pk_mul_f32 v[12:13], v[12:13], v[16:17]
	s_nop 0
	v_cvt_pk_bf16_f32 v122, v12, v13
	v_pk_mul_f32 v[12:13], v[86:87], v[90:91] op_sel_hi:[0,1]
	v_pk_mul_f32 v[12:13], v[14:15], v[12:13]
	s_nop 0
	v_cvt_pk_bf16_f32 v123, v12, v13
	v_pk_mul_f32 v[12:13], v[86:87], v[88:89] op_sel_hi:[0,1]
	v_pk_mul_f32 v[8:9], v[8:9], v[12:13]
	s_nop 0
	v_cvt_pk_bf16_f32 v124, v8, v9
	v_lshl_add_u64 v[8:9], v[180:181], 0, s[16:17]
	global_load_dwordx4 v[130:133], v[8:9], off
	v_pk_mul_f32 v[8:9], v[86:87], v[84:85] op_sel_hi:[0,1]
	v_pk_mul_f32 v[8:9], v[10:11], v[8:9]
	s_mov_b64 s[16:17], 0
	v_cvt_pk_bf16_f32 v125, v8, v9
	v_pk_mul_f32 v[8:9], v[86:87], v[82:83] op_sel_hi:[0,1]
	s_waitcnt vmcnt(10)
	v_pk_mul_f32 v[4:5], v[4:5], v[8:9]
	s_waitcnt vmcnt(1)
	v_lshlrev_b32_e32 v18, 16, v114
	v_cvt_pk_bf16_f32 v126, v4, v5
	v_pk_mul_f32 v[4:5], v[86:87], v[80:81] op_sel_hi:[0,1]
	v_pk_mul_f32 v[4:5], v[6:7], v[4:5]
	v_and_b32_e32 v19, 0xffff0000, v114
	v_cvt_pk_bf16_f32 v127, v4, v5
	v_pk_mul_f32 v[4:5], v[86:87], v[78:79] op_sel_hi:[0,1]
	v_pk_mul_f32 v[0:1], v[0:1], v[4:5]
	v_lshl_add_u64 v[4:5], v[176:177], 0, s[18:19]
	v_cvt_pk_bf16_f32 v128, v0, v1
	v_pk_mul_f32 v[0:1], v[86:87], v[76:77] op_sel_hi:[0,1]
	v_pk_mul_f32 v[0:1], v[2:3], v[0:1]
	v_lshl_add_u64 v[2:3], v[182:183], 0, s[18:19]
	v_cvt_pk_bf16_f32 v129, v0, v1
	v_pk_mul_f32 v[0:1], v[86:87], v[74:75] op_sel_hi:[0,1]
	v_pk_mul_f32 v[0:1], v[140:141], v[0:1]
	v_lshlrev_b32_e32 v14, 16, v115
	v_cvt_pk_bf16_f32 v134, v0, v1
	v_pk_mul_f32 v[0:1], v[86:87], v[72:73] op_sel_hi:[0,1]
	v_pk_mul_f32 v[0:1], v[142:143], v[0:1]
	v_and_b32_e32 v15, 0xffff0000, v115
	v_cvt_pk_bf16_f32 v135, v0, v1
	v_pk_mul_f32 v[0:1], v[86:87], v[70:71] op_sel_hi:[0,1]
	v_pk_mul_f32 v[0:1], v[136:137], v[0:1]
	v_pk_mul_f32 v[20:21], v[18:19], v[18:19]
	v_cvt_pk_bf16_f32 v136, v0, v1
	v_pk_mul_f32 v[0:1], v[86:87], v[68:69] op_sel_hi:[0,1]
	v_pk_mul_f32 v[0:1], v[138:139], v[0:1]
	v_pk_mul_f32 v[16:17], v[14:15], v[14:15]
	v_cvt_pk_bf16_f32 v137, v0, v1
	v_pk_mul_f32 v[0:1], v[86:87], v[66:67] op_sel_hi:[0,1]
	v_pk_mul_f32 v[0:1], v[144:145], v[0:1]
	v_add_f32_e32 v20, v20, v21
	v_cvt_pk_bf16_f32 v138, v0, v1
	v_pk_mul_f32 v[0:1], v[86:87], v[64:65] op_sel_hi:[0,1]
	v_pk_mul_f32 v[0:1], v[146:147], v[0:1]
	global_load_dwordx4 v[146:149], v[2:3], off
	global_load_dwordx4 v[150:153], v[4:5], off
	v_lshlrev_b32_e32 v10, 16, v116
	v_and_b32_e32 v11, 0xffff0000, v116
	v_add_f32_e32 v16, v16, v20
	v_pk_mul_f32 v[12:13], v[10:11], v[10:11]
	v_add_f32_e32 v16, v17, v16
	v_lshlrev_b32_e32 v6, 16, v117
	v_and_b32_e32 v7, 0xffff0000, v117
	v_add_f32_e32 v12, v12, v16
	v_pk_mul_f32 v[8:9], v[6:7], v[6:7]
	v_add_f32_e32 v12, v13, v12
	v_add_f32_e32 v8, v8, v12
	v_add_f32_e32 v8, v9, v8
	s_nop 1
	v_mov_b32_dpp v9, v8 quad_perm:[1,0,3,2] row_mask:0xf bank_mask:0xf
	v_cvt_pk_bf16_f32 v139, v0, v1
	v_pk_mul_f32 v[0:1], v[86:87], v[62:63] op_sel_hi:[0,1]
	v_pk_mul_f32 v[0:1], v[44:45], v[0:1]
	s_waitcnt vmcnt(2)
	v_lshlrev_b32_e32 v20, 16, v130
	s_waitcnt lgkmcnt(0)
	v_add_f32_e32 v2, v8, v9
	s_nop 1
	v_mov_b32_dpp v3, v2 quad_perm:[2,3,0,1] row_mask:0xf bank_mask:0xf
	v_cvt_pk_bf16_f32 v140, v0, v1
	v_pk_mul_f32 v[0:1], v[86:87], v[60:61] op_sel_hi:[0,1]
	v_pk_mul_f32 v[0:1], v[46:47], v[0:1]
	v_and_b32_e32 v21, 0xffff0000, v130
	s_waitcnt lgkmcnt(0)
	v_add_f32_e32 v2, v2, v3
	s_nop 1
	v_mov_b32_dpp v3, v2 row_shl:4 row_mask:0xf bank_mask:0x5
	v_mov_b32_dpp v3, v2 row_shr:4 row_mask:0xf bank_mask:0xa
	v_cvt_pk_bf16_f32 v141, v0, v1
	v_pk_mul_f32 v[0:1], v[86:87], v[58:59] op_sel_hi:[0,1]
	v_pk_mul_f32 v[0:1], v[40:41], v[0:1]
	v_lshlrev_b32_e32 v12, 16, v131
	v_and_b32_e32 v13, 0xffff0000, v131
	v_pk_mul_f32 v[22:23], v[20:21], v[20:21]
	v_cvt_pk_bf16_f32 v142, v0, v1
	v_pk_mul_f32 v[0:1], v[86:87], v[56:57] op_sel_hi:[0,1]
	v_pk_mul_f32 v[16:17], v[12:13], v[12:13]
	v_add_f32_e32 v22, v22, v23
	v_pk_mul_f32 v[0:1], v[42:43], v[0:1]
	v_lshlrev_b32_e32 v8, 16, v132
	v_and_b32_e32 v9, 0xffff0000, v132
	v_add_f32_e32 v16, v16, v22
	v_cvt_pk_bf16_f32 v143, v0, v1
	v_pk_mul_f32 v[0:1], v[86:87], v[54:55] op_sel_hi:[0,1]
	s_waitcnt lgkmcnt(0)
; #define LAS __attribute__((address_space(3)))
; __device__ __forceinline__ unsigned pk2(float lo, float hi) { f32x2 v = {lo, hi}; bf16x2_t b = __builtin_convertvector(v, bf16x2_t); return __builtin_bit_cast(unsigned, b); }
; __device__ __forceinline__ float bflo(unsigned w) { return __uint_as_float(w << 16); }
; __device__ __forceinline__ float bfhi(unsigned w) { return __uint_as_float(w & 0xffff0000u); }
; __device__ __forceinline__ u32x4 knorm8(u32x4 w, const f32x4 ga, const f32x4 gb) {
;     float v[8];
; #pragma unroll
;     for (int q = 0; q < 4; ++q) { v[2 * q] = bflo(w[q]); v[2 * q + 1] = bfhi(w[q]); }
;     float ss = 0.f;
; #pragma unroll
;     for (int e = 0; e < 8; ++e) ss += v[e] * v[e];
;     ss += __shfl_xor(ss, 1); ss += __shfl_xor(ss, 2); ss += __shfl_xor(ss, 4); ss += __shfl_xor(ss, 8);
;     const float r = __builtin_amdgcn_rsqf(ss * (1.0f / HD) + RMS_EPS);
;     u32x4 o; o.x = pk2(v[0] * r * ga[0], v[1] * r * ga[1]); o.y = pk2(v[2] * r * ga[2], v[3] * r * ga[3]); o.z = pk2(v[4] * r * gb[0], v[5] * r * gb[1]); o.w = pk2(v[6] * r * gb[2], v[7] * r * gb[3]);
;     return o;
; }
; __device__ __forceinline__ void attn_unit(int b, int h, int qb, const bf16_t* __restrict__ QK, const bf16_t* __restrict__ VT, bf16_t* __restrict__ O, const float* __restrict__ qg, const float* __restrict__ kg, ...
;     ...
;     f32x16 o[4];
; #pragma unroll
;     for (int d = 0; d < 4; ++d)
; #pragma unroll
;         for (int r = 0; r < 16; ++r) o[d][r] = 0.f;
;     float R = 0.f; bool wdone = false;
;     u32x4 sk0, sk1, sv0, sv1;
;     { const int kt = NT - 1; sk0 = *(const u32x4*)(kg0 + (size_t)kt * 64 * 4096); sk1 = *(const u32x4*)(kg1 + (size_t)kt * 64 * 4096); sv0 = *(const u32x4*)(vg0 + kt * 64); sv1 = *(const u32x4*)(vg1 + kt * 64); }
;     *(LAS u32x4*)(Kb + kl0) = knorm8(sk0, kga, kgb); *(LAS u32x4*)(Kb + kl1) = knorm8(sk1, kga, kgb); *(LAS u32x4*)(Vb + vl0) = sv0; *(LAS u32x4*)(Vb + vl1) = sv1;
;     __syncthreads();
;     int buf = 0;
	v_add_f32_e32 v24, v2, v3
	v_pk_mul_f32 v[2:3], v[8:9], v[8:9]
	v_add_f32_e32 v16, v17, v16
	v_pk_mul_f32 v[0:1], v[36:37], v[0:1]
	v_lshlrev_b32_e32 v4, 16, v133
	v_and_b32_e32 v5, 0xffff0000, v133
	v_add_f32_e32 v2, v2, v16
	v_cvt_pk_bf16_f32 v144, v0, v1
	v_pk_mul_f32 v[0:1], v[4:5], v[4:5]
	v_add_f32_e32 v2, v3, v2
	v_add_f32_e32 v0, v0, v2
	v_add_f32_e32 v2, v1, v0
	s_nop 1
	v_mov_b32_dpp v25, v24 row_ror:8 row_mask:0xf bank_mask:0xf
	s_nop 1
	v_mov_b32_dpp v3, v2 quad_perm:[1,0,3,2] row_mask:0xf bank_mask:0xf
	v_pk_mul_f32 v[0:1], v[86:87], v[52:53] op_sel_hi:[0,1]
	v_pk_mul_f32 v[0:1], v[38:39], v[0:1]
	s_mov_b32 s18, s3
	s_waitcnt lgkmcnt(1)
	v_add_f32_e32 v16, v24, v25
	s_waitcnt lgkmcnt(0)
	v_add_f32_e32 v2, v2, v3
	v_fmamk_f32 v16, v16, 0x3c000000, v243
	s_nop 1
	v_mov_b32_dpp v3, v2 quad_perm:[2,3,0,1] row_mask:0xf bank_mask:0xf
	v_rsq_f32_e32 v16, v16
	v_cvt_pk_bf16_f32 v145, v0, v1
	v_pk_mul_f32 v[0:1], v[16:17], v[18:19] op_sel_hi:[0,1]
	s_waitcnt lgkmcnt(0)
	v_add_f32_e32 v17, v2, v3
	s_nop 1
	v_mov_b32_dpp v18, v17 row_shl:4 row_mask:0xf bank_mask:0x5
	v_mov_b32_dpp v18, v17 row_shr:4 row_mask:0xf bank_mask:0xa
	v_pk_mul_f32 v[2:3], v[16:17], v[14:15] op_sel_hi:[0,1]
	v_pk_mul_f32 v[0:1], v[102:103], v[0:1]
	v_pk_mul_f32 v[2:3], v[104:105], v[2:3]
	v_cvt_pk_bf16_f32 v0, v0, v1
	s_waitcnt lgkmcnt(0)
	v_add_f32_e32 v14, v17, v18
	s_nop 1
	v_mov_b32_dpp v15, v14 row_ror:8 row_mask:0xf bank_mask:0xf
	v_cvt_pk_bf16_f32 v1, v2, v3
	v_pk_mul_f32 v[2:3], v[16:17], v[10:11] op_sel_hi:[0,1]
	v_pk_mul_f32 v[2:3], v[98:99], v[2:3]
	v_pk_mul_f32 v[6:7], v[16:17], v[6:7] op_sel_hi:[0,1]
	v_cvt_pk_bf16_f32 v2, v2, v3
	s_waitcnt lgkmcnt(0)
	v_add_f32_e32 v3, v14, v15
	v_fmamk_f32 v3, v3, 0x3c000000, v243
	v_rsq_f32_e32 v10, v3
	v_pk_mul_f32 v[6:7], v[100:101], v[6:7]
	v_mov_b32_e32 v14, v97
	v_cvt_pk_bf16_f32 v3, v6, v7
	ds_write_b128 v171, v[0:3]
	v_pk_mul_f32 v[0:1], v[10:11], v[20:21] op_sel_hi:[0,1]
	v_pk_mul_f32 v[2:3], v[10:11], v[12:13] op_sel_hi:[0,1]
	v_pk_mul_f32 v[0:1], v[102:103], v[0:1]
	v_pk_mul_f32 v[2:3], v[104:105], v[2:3]
	v_cvt_pk_bf16_f32 v0, v0, v1
	v_cvt_pk_bf16_f32 v1, v2, v3
	v_pk_mul_f32 v[2:3], v[10:11], v[8:9] op_sel_hi:[0,1]
	v_pk_mul_f32 v[4:5], v[10:11], v[4:5] op_sel_hi:[0,1]
	v_pk_mul_f32 v[2:3], v[98:99], v[2:3]
	v_pk_mul_f32 v[4:5], v[100:101], v[4:5]
	v_cvt_pk_bf16_f32 v2, v2, v3
	v_cvt_pk_bf16_f32 v3, v4, v5
	v_mov_b32_e32 v15, v97
	ds_write_b128 v184, v[0:3]
	s_waitcnt vmcnt(1)
	ds_write_b128 v192, v[146:149] offset:34816
	s_waitcnt vmcnt(0)
	ds_write_b128 v193, v[150:153] offset:34816
	v_mov_b32_e32 v0, v97
	v_mov_b32_e32 v1, v97
	v_mov_b32_e32 v2, v97
	v_mov_b32_e32 v3, v97
	v_mov_b32_e32 v4, v97
	v_mov_b32_e32 v5, v97
	v_mov_b32_e32 v6, v97
	v_mov_b32_e32 v7, v97
	v_mov_b32_e32 v8, v97
	v_mov_b32_e32 v9, v97
	v_mov_b32_e32 v10, v97
	v_mov_b32_e32 v11, v97
	v_mov_b32_e32 v12, v97
	v_mov_b32_e32 v13, v97
	v_mov_b64_e32 v[62:63], v[14:15]
	v_mov_b64_e32 v[46:47], v[14:15]
	v_mov_b64_e32 v[30:31], v[14:15]
	v_mov_b64_e32 v[60:61], v[12:13]
	v_mov_b64_e32 v[58:59], v[10:11]
	v_mov_b64_e32 v[56:57], v[8:9]
	v_mov_b64_e32 v[54:55], v[6:7]
	v_mov_b64_e32 v[52:53], v[4:5]
	v_mov_b64_e32 v[50:51], v[2:3]
	v_mov_b64_e32 v[48:49], v[0:1]
	v_mov_b64_e32 v[44:45], v[12:13]
	v_mov_b64_e32 v[42:43], v[10:11]
	v_mov_b64_e32 v[40:41], v[8:9]
	v_mov_b64_e32 v[38:39], v[6:7]
	v_mov_b64_e32 v[36:37], v[4:5]
	v_mov_b64_e32 v[34:35], v[2:3]
	v_mov_b64_e32 v[32:33], v[0:1]
	v_mov_b64_e32 v[28:29], v[12:13]
	v_mov_b64_e32 v[26:27], v[10:11]
	v_mov_b64_e32 v[24:25], v[8:9]
	v_mov_b64_e32 v[22:23], v[6:7]
	v_mov_b64_e32 v[20:21], v[4:5]
	v_mov_b64_e32 v[18:19], v[2:3]
	v_mov_b64_e32 v[16:17], v[0:1]
	s_waitcnt lgkmcnt(0)
	s_barrier
	s_branch .LBB0_479

; #define LAS __attribute__((address_space(3)))
; __device__ __forceinline__ unsigned pk2(float lo, float hi) { f32x2 v = {lo, hi}; bf16x2_t b = __builtin_convertvector(v, bf16x2_t); return __builtin_bit_cast(unsigned, b); }
; __device__ __forceinline__ float bflo(unsigned w) { return __uint_as_float(w << 16); }
; __device__ __forceinline__ float bfhi(unsigned w) { return __uint_as_float(w & 0xffff0000u); }
; __device__ __forceinline__ u32x4 knorm8(u32x4 w, const f32x4 ga, const f32x4 gb) {
;     float v[8];
; #pragma unroll
;     for (int q = 0; q < 4; ++q) { v[2 * q] = bflo(w[q]); v[2 * q + 1] = bfhi(w[q]); }
;     float ss = 0.f;
; #pragma unroll
;     for (int e = 0; e < 8; ++e) ss += v[e] * v[e];
;     ss += __shfl_xor(ss, 1); ss += __shfl_xor(ss, 2); ss += __shfl_xor(ss, 4); ss += __shfl_xor(ss, 8);
;     const float r = __builtin_amdgcn_rsqf(ss * (1.0f / HD) + RMS_EPS);
;     u32x4 o; o.x = pk2(v[0] * r * ga[0], v[1] * r * ga[1]); o.y = pk2(v[2] * r * ga[2], v[3] * r * ga[3]); o.z = pk2(v[4] * r * gb[0], v[5] * r * gb[1]); o.w = pk2(v[6] * r * gb[2], v[7] * r * gb[3]);
;     return o;
; __device__ __forceinline__ void attn_unit(int b, int h, int qb, const bf16_t* __restrict__ QK, const bf16_t* __restrict__ VT, bf16_t* __restrict__ O, const float* __restrict__ qg, const float* __restrict__ kg, ...
;     ...
;         if (kt > 0) { const int nb = buf ^ 1; *(LAS u32x4*)(Kb + nb * AK_BUF + kl0) = knorm8(sk0, kga, kgb); *(LAS u32x4*)(Kb + nb * AK_BUF + kl1) = knorm8(sk1, kga, kgb); *(LAS u32x4*)(Vb + nb * AV_BUF + vl0) = sv0; *(LAS u32x4*)(Vb + nb * AV_BUF + vl1) = sv1; }
.LBB0_486:
	s_or_b64 exec, exec, s[52:53]
	s_andn2_b64 vcc, exec, s[60:61]
	s_cbranch_vccnz .LBB0_477
	s_waitcnt vmcnt(3)
	v_lshlrev_b32_e32 v76, 16, v114
	v_and_b32_e32 v77, 0xffff0000, v114
	v_lshlrev_b32_e32 v72, 16, v115
	v_and_b32_e32 v73, 0xffff0000, v115
	v_pk_mul_f32 v[78:79], v[76:77], v[76:77]
	v_pk_mul_f32 v[74:75], v[72:73], v[72:73]
	v_add_f32_e32 v78, v78, v79
	v_lshlrev_b32_e32 v66, 16, v116
	v_and_b32_e32 v67, 0xffff0000, v116
	v_add_f32_e32 v74, v74, v78
	v_pk_mul_f32 v[70:71], v[66:67], v[66:67]
	v_add_f32_e32 v74, v75, v74
	v_lshlrev_b32_e32 v68, 16, v117
	v_and_b32_e32 v69, 0xffff0000, v117
	v_add_f32_e32 v70, v70, v74
	v_pk_mul_f32 v[64:65], v[68:69], v[68:69]
	v_add_f32_e32 v70, v71, v70
	v_add_f32_e32 v64, v64, v70
	v_add_f32_e32 v64, v65, v64
	s_nop 1
	v_mov_b32_dpp v65, v64 quad_perm:[1,0,3,2] row_mask:0xf bank_mask:0xf
	s_xor_b32 s3, s24, 1
	s_mul_i32 s26, s3, 0x4400
	s_add_i32 s26, s26, 0
	s_lshl_b32 s3, s3, 10
	s_waitcnt lgkmcnt(0)
	v_add_f32_e32 v64, v64, v65
	s_nop 1
	v_mov_b32_dpp v65, v64 quad_perm:[2,3,0,1] row_mask:0xf bank_mask:0xf
	s_waitcnt lgkmcnt(0)
	v_add_f32_e32 v64, v64, v65
	s_nop 1
	v_mov_b32_dpp v65, v64 row_shl:4 row_mask:0xf bank_mask:0x5
	v_mov_b32_dpp v65, v64 row_shr:4 row_mask:0xf bank_mask:0xa
	s_waitcnt lgkmcnt(0)
	v_add_f32_e32 v64, v64, v65
	s_nop 1
	v_mov_b32_dpp v65, v64 row_ror:8 row_mask:0xf bank_mask:0xf
	s_waitcnt lgkmcnt(0)
	v_add_f32_e32 v64, v64, v65
	v_fmamk_f32 v64, v64, 0x3c000000, v243
	v_rsq_f32_e32 v70, v64
	s_nop 0
	v_pk_mul_f32 v[64:65], v[70:71], v[76:77] op_sel_hi:[0,1]
	v_pk_mul_f32 v[72:73], v[70:71], v[72:73] op_sel_hi:[0,1]
	v_pk_mul_f32 v[64:65], v[102:103], v[64:65]
	v_pk_mul_f32 v[72:73], v[104:105], v[72:73]
	v_pk_mul_f32 v[66:67], v[70:71], v[66:67] op_sel_hi:[0,1]
	v_pk_mul_f32 v[68:69], v[70:71], v[68:69] op_sel_hi:[0,1]
	s_waitcnt vmcnt(2)
	v_lshlrev_b32_e32 v76, 16, v130
	v_and_b32_e32 v77, 0xffff0000, v130
	v_cvt_pk_bf16_f32 v64, v64, v65
	v_cvt_pk_bf16_f32 v65, v72, v73
	v_pk_mul_f32 v[66:67], v[98:99], v[66:67]
	v_pk_mul_f32 v[68:69], v[100:101], v[68:69]
	v_lshlrev_b32_e32 v72, 16, v131
	v_and_b32_e32 v73, 0xffff0000, v131
	v_pk_mul_f32 v[78:79], v[76:77], v[76:77]
	v_cvt_pk_bf16_f32 v66, v66, v67
	v_cvt_pk_bf16_f32 v67, v68, v69
	v_add_u32_e32 v68, s26, v164
	v_pk_mul_f32 v[74:75], v[72:73], v[72:73]
	v_add_f32_e32 v78, v78, v79
	ds_write_b128 v68, v[64:67]
	v_lshlrev_b32_e32 v66, 16, v132
	v_and_b32_e32 v67, 0xffff0000, v132
	v_add_f32_e32 v74, v74, v78
	v_pk_mul_f32 v[70:71], v[66:67], v[66:67]
	v_add_f32_e32 v74, v75, v74
	v_lshlrev_b32_e32 v68, 16, v133
	v_and_b32_e32 v69, 0xffff0000, v133
	v_add_f32_e32 v70, v70, v74
	v_pk_mul_f32 v[64:65], v[68:69], v[68:69]
	v_add_f32_e32 v70, v71, v70
	v_add_f32_e32 v64, v64, v70
	v_add_f32_e32 v64, v65, v64
	s_nop 1
	v_mov_b32_dpp v65, v64 quad_perm:[1,0,3,2] row_mask:0xf bank_mask:0xf
	s_waitcnt lgkmcnt(0)
	v_add_f32_e32 v64, v64, v65
	s_nop 1
	v_mov_b32_dpp v65, v64 quad_perm:[2,3,0,1] row_mask:0xf bank_mask:0xf
	s_waitcnt lgkmcnt(0)
	v_add_f32_e32 v64, v64, v65
	s_nop 1
	v_mov_b32_dpp v65, v64 row_shl:4 row_mask:0xf bank_mask:0x5
	v_mov_b32_dpp v65, v64 row_shr:4 row_mask:0xf bank_mask:0xa
	s_waitcnt lgkmcnt(0)
	v_add_f32_e32 v64, v64, v65
	s_nop 1
	v_mov_b32_dpp v65, v64 row_ror:8 row_mask:0xf bank_mask:0xf
	s_waitcnt lgkmcnt(0)
	v_add_f32_e32 v64, v64, v65
	v_fmamk_f32 v64, v64, 0x3c000000, v243
	v_rsq_f32_e32 v70, v64
	s_nop 0
	v_pk_mul_f32 v[64:65], v[70:71], v[76:77] op_sel_hi:[0,1]
	v_pk_mul_f32 v[72:73], v[70:71], v[72:73] op_sel_hi:[0,1]
	v_pk_mul_f32 v[66:67], v[70:71], v[66:67] op_sel_hi:[0,1]
	v_pk_mul_f32 v[68:69], v[70:71], v[68:69] op_sel_hi:[0,1]
	v_pk_mul_f32 v[64:65], v[102:103], v[64:65]
	v_pk_mul_f32 v[72:73], v[104:105], v[72:73]
	v_pk_mul_f32 v[66:67], v[98:99], v[66:67]
	v_pk_mul_f32 v[68:69], v[100:101], v[68:69]
	v_cvt_pk_bf16_f32 v64, v64, v65
	v_cvt_pk_bf16_f32 v65, v72, v73
	v_cvt_pk_bf16_f32 v66, v66, v67
	v_cvt_pk_bf16_f32 v67, v68, v69
	v_add_u32_e32 v68, s26, v156
	s_add_i32 s26, s26, s3
	ds_write_b128 v68, v[64:67]
	v_add_u32_e32 v64, s26, v160
	s_waitcnt vmcnt(1)
	ds_write_b128 v64, v[146:149] offset:34816
	v_add_u32_e32 v64, s26, v166
	s_waitcnt vmcnt(0)
	ds_write_b128 v64, v[150:153] offset:34816
	s_branch .LBB0_477
